# v10 + K-loops: redundant lgkmcnt(0) after barrier deleted; GEMM1 r0 prefetch issued after SP1 barrier
# baseline (speedup 1.0000x reference)
.LBB0_439:
	ds_read_b128 v[128:131], v192
	ds_read_b128 v[132:135], v192 offset:1024
	ds_read_b128 v[136:139], v192 offset:2048
	ds_read_b128 v[158:161], v192 offset:3072
	ds_read_b128 v[168:171], v193
	ds_read_b128 v[172:175], v193 offset:1024
	ds_read_b128 v[196:199], v193 offset:2048
	ds_read_b128 v[200:203], v193 offset:3072
	s_add_u32 s66, s64, 0xfffc0080
	s_addc_u32 s67, s65, -1
	s_cmp_eq_u32 s86, 12
	s_cselect_b32 s69, s53, s67
	s_cselect_b32 s68, s57, s66
	s_cselect_b32 s67, s55, s85
	s_cselect_b32 s66, s63, s84
	s_cselect_b32 s98, 1, 0
	v_lshl_add_u64 v[162:163], s[64:65], 0, v[150:151]
	s_add_i32 m0, s70, 0xc000
	ds_read_b128 v[204:207], v194
	ds_read_b128 v[208:211], v194 offset:1024
	ds_read_b128 v[212:215], v194 offset:2048
	ds_read_b128 v[216:219], v194 offset:3072
	ds_read_b128 v[220:223], v194 offset:4096
	ds_read_b128 v[224:227], v194 offset:5120
	ds_read_b128 v[228:231], v194 offset:6144
	ds_read_b128 v[232:235], v194 offset:7168
	global_load_lds_dwordx4 v[162:163], off
	v_lshl_add_u64 v[162:163], s[64:65], 0, v[152:153]
	s_add_i32 m0, s70, 0xe000
	s_nop 0
	global_load_lds_dwordx4 v[162:163], off
	s_waitcnt vmcnt(8)
	s_waitcnt lgkmcnt(0)
	s_barrier
	s_cmp_lg_u32 s98, 0
	s_cbranch_scc0 .Lg1_nopf
	s_lshl_b32 s99, s52, 8
	v_add_u32_e32 v240, s99, v165
	v_ashrrev_i32_e32 v241, 31, v240
	v_lshl_add_u64 v[240:241], v[240:241], 2, s[20:21]
	global_load_dword v242, v[240:241], off
	global_load_dword v243, v[240:241], off offset:64
	global_load_dword v244, v[240:241], off offset:128
	global_load_dword v245, v[240:241], off offset:192
	global_load_dword v246, v[240:241], off offset:512
	global_load_dword v248, v[240:241], off offset:576
	global_load_dword v249, v[240:241], off offset:640
	global_load_dword v250, v[240:241], off offset:704
.Lg1_nopf:
	s_setprio 1
	v_mfma_f32_16x16x32_bf16 v[124:127], v[128:131], v[204:207], v[124:127]
	v_mfma_f32_16x16x32_bf16 v[120:123], v[136:139], v[204:207], v[120:123]
	v_mfma_f32_16x16x32_bf16 v[96:99], v[128:131], v[212:215], v[96:99]
	v_mfma_f32_16x16x32_bf16 v[88:91], v[136:139], v[212:215], v[88:91]
	v_mfma_f32_16x16x32_bf16 v[76:79], v[128:131], v[220:223], v[76:79]
	v_mfma_f32_16x16x32_bf16 v[72:75], v[136:139], v[220:223], v[72:75]
	v_mfma_f32_16x16x32_bf16 v[60:63], v[128:131], v[228:231], v[60:63]
	v_mfma_f32_16x16x32_bf16 v[108:111], v[136:139], v[228:231], v[108:111]
	v_mfma_f32_16x16x32_bf16 v[124:127], v[132:135], v[208:211], v[124:127]
	v_mfma_f32_16x16x32_bf16 v[120:123], v[158:161], v[208:211], v[120:123]
	v_mfma_f32_16x16x32_bf16 v[96:99], v[132:135], v[216:219], v[96:99]
	v_mfma_f32_16x16x32_bf16 v[88:91], v[158:161], v[216:219], v[88:91]
	v_mfma_f32_16x16x32_bf16 v[76:79], v[132:135], v[224:227], v[76:79]
	v_mfma_f32_16x16x32_bf16 v[72:75], v[158:161], v[224:227], v[72:75]
	v_mfma_f32_16x16x32_bf16 v[60:63], v[132:135], v[232:235], v[60:63]
	v_mfma_f32_16x16x32_bf16 v[108:111], v[158:161], v[232:235], v[108:111]
	s_setprio 0
	s_setprio 1
	v_mfma_f32_16x16x32_bf16 v[116:119], v[168:171], v[204:207], v[116:119]
	v_mfma_f32_16x16x32_bf16 v[112:115], v[196:199], v[204:207], v[112:115]
	v_mfma_f32_16x16x32_bf16 v[84:87], v[168:171], v[212:215], v[84:87]
	v_mfma_f32_16x16x32_bf16 v[80:83], v[196:199], v[212:215], v[80:83]
	v_mfma_f32_16x16x32_bf16 v[68:71], v[168:171], v[220:223], v[68:71]
	v_mfma_f32_16x16x32_bf16 v[64:67], v[196:199], v[220:223], v[64:67]
	v_mfma_f32_16x16x32_bf16 v[104:107], v[168:171], v[228:231], v[104:107]
	v_mfma_f32_16x16x32_bf16 v[56:59], v[196:199], v[228:231], v[56:59]
	v_mfma_f32_16x16x32_bf16 v[116:119], v[172:175], v[208:211], v[116:119]
	v_mfma_f32_16x16x32_bf16 v[112:115], v[200:203], v[208:211], v[112:115]
	v_mfma_f32_16x16x32_bf16 v[84:87], v[172:175], v[216:219], v[84:87]
	v_mfma_f32_16x16x32_bf16 v[80:83], v[200:203], v[216:219], v[80:83]
	v_mfma_f32_16x16x32_bf16 v[68:71], v[172:175], v[224:227], v[68:71]
	v_mfma_f32_16x16x32_bf16 v[64:67], v[200:203], v[224:227], v[64:67]
	v_mfma_f32_16x16x32_bf16 v[104:107], v[172:175], v[232:235], v[104:107]
	v_mfma_f32_16x16x32_bf16 v[56:59], v[200:203], v[232:235], v[56:59]
	s_setprio 0
	s_barrier
	s_add_i32 s87, s82, s23
	v_lshl_add_u64 v[162:163], s[66:67], 0, v[140:141]
	s_mov_b32 m0, s87
	ds_read_b128 v[204:207], v194 offset:16384
	ds_read_b128 v[208:211], v194 offset:17408
	ds_read_b128 v[212:215], v194 offset:18432
	ds_read_b128 v[216:219], v194 offset:19456
	ds_read_b128 v[220:223], v194 offset:20480
	ds_read_b128 v[224:227], v194 offset:21504
	ds_read_b128 v[228:231], v194 offset:22528
	ds_read_b128 v[232:235], v194 offset:23552
	global_load_lds_dwordx4 v[162:163], off
	s_add_i32 m0, s87, 0x2000
	s_add_u32 s88, s66, 0x40000
	v_lshl_add_u64 v[178:179], s[66:67], 0, v[142:143]
	s_addc_u32 s89, s67, 0
	s_add_i32 s87, s83, s23
	global_load_lds_dwordx4 v[178:179], off
	v_lshl_add_u64 v[184:185], s[88:89], 0, v[140:141]
	s_mov_b32 m0, s87
	v_lshl_add_u64 v[236:237], s[68:69], 0, v[142:143]
	global_load_lds_dwordx4 v[184:185], off
	v_lshl_add_u64 v[184:185], s[88:89], 0, v[142:143]
	s_add_i32 m0, s87, 0x2000
	s_nop 0
	global_load_lds_dwordx4 v[184:185], off
	v_lshl_add_u64 v[184:185], s[68:69], 0, v[140:141]
	s_mov_b32 m0, s70
	s_nop 0
	global_load_lds_dwordx4 v[184:185], off
	s_mov_b32 m0, s71
	s_nop 0
	global_load_lds_dwordx4 v[236:237], off
	s_waitcnt vmcnt(8)
	s_waitcnt lgkmcnt(0)
	s_barrier
	s_setprio 1
	v_mfma_f32_16x16x32_bf16 v[52:55], v[128:131], v[204:207], v[52:55]
	v_mfma_f32_16x16x32_bf16 v[48:51], v[136:139], v[204:207], v[48:51]
	v_mfma_f32_16x16x32_bf16 v[16:19], v[128:131], v[212:215], v[16:19]
	v_mfma_f32_16x16x32_bf16 v[8:11], v[136:139], v[212:215], v[8:11]
	v_mfma_f32_16x16x32_bf16 v[28:31], v[128:131], v[220:223], v[28:31]
	v_mfma_f32_16x16x32_bf16 v[24:27], v[136:139], v[220:223], v[24:27]
	v_mfma_f32_16x16x32_bf16 v[36:39], v[128:131], v[228:231], v[36:39]
	v_mfma_f32_16x16x32_bf16 v[100:103], v[136:139], v[228:231], v[100:103]
	v_mfma_f32_16x16x32_bf16 v[52:55], v[132:135], v[208:211], v[52:55]
	v_mfma_f32_16x16x32_bf16 v[48:51], v[158:161], v[208:211], v[48:51]
	v_mfma_f32_16x16x32_bf16 v[16:19], v[132:135], v[216:219], v[16:19]
	v_mfma_f32_16x16x32_bf16 v[8:11], v[158:161], v[216:219], v[8:11]
	v_mfma_f32_16x16x32_bf16 v[28:31], v[132:135], v[224:227], v[28:31]
	v_mfma_f32_16x16x32_bf16 v[24:27], v[158:161], v[224:227], v[24:27]
	v_mfma_f32_16x16x32_bf16 v[36:39], v[132:135], v[232:235], v[36:39]
	v_mfma_f32_16x16x32_bf16 v[100:103], v[158:161], v[232:235], v[100:103]
	s_setprio 0
	s_setprio 1
	v_mfma_f32_16x16x32_bf16 v[44:47], v[168:171], v[204:207], v[44:47]
	v_mfma_f32_16x16x32_bf16 v[40:43], v[196:199], v[204:207], v[40:43]
	v_mfma_f32_16x16x32_bf16 v[0:3], v[168:171], v[212:215], v[0:3]
	v_mfma_f32_16x16x32_bf16 v[4:7], v[196:199], v[212:215], v[4:7]
	v_mfma_f32_16x16x32_bf16 v[12:15], v[168:171], v[220:223], v[12:15]
	v_mfma_f32_16x16x32_bf16 v[20:23], v[196:199], v[220:223], v[20:23]
	v_mfma_f32_16x16x32_bf16 v[92:95], v[168:171], v[228:231], v[92:95]
	v_mfma_f32_16x16x32_bf16 v[32:35], v[196:199], v[228:231], v[32:35]
	v_mfma_f32_16x16x32_bf16 v[44:47], v[172:175], v[208:211], v[44:47]
	v_mfma_f32_16x16x32_bf16 v[40:43], v[200:203], v[208:211], v[40:43]
	v_mfma_f32_16x16x32_bf16 v[0:3], v[172:175], v[216:219], v[0:3]
	v_mfma_f32_16x16x32_bf16 v[4:7], v[200:203], v[216:219], v[4:7]
	v_mfma_f32_16x16x32_bf16 v[12:15], v[172:175], v[224:227], v[12:15]
	v_mfma_f32_16x16x32_bf16 v[20:23], v[200:203], v[224:227], v[20:23]
	v_mfma_f32_16x16x32_bf16 v[92:95], v[172:175], v[232:235], v[92:95]
	v_mfma_f32_16x16x32_bf16 v[32:35], v[200:203], v[232:235], v[32:35]
	s_setprio 0
	s_barrier
	s_add_i32 s87, 0, 0x18000
	s_add_i32 s88, 0, 0x1c000
	v_add_u32_e32 v158, s87, v167
	v_add_u32_e32 v164, s88, v167
	ds_read_b128 v[128:131], v158
	ds_read_b128 v[132:135], v158 offset:1024
	ds_read_b128 v[136:139], v158 offset:2048
	ds_read_b128 v[158:161], v158 offset:3072
	ds_read_b128 v[168:171], v164
	ds_read_b128 v[172:175], v164 offset:1024
	ds_read_b128 v[196:199], v164 offset:2048
	ds_read_b128 v[200:203], v164 offset:3072
	s_add_u32 s68, s68, 0x40000
	s_addc_u32 s69, s69, 0
	s_mov_b32 m0, s72
	v_lshl_add_u64 v[238:239], s[68:69], 0, v[140:141]
	ds_read_b128 v[204:207], v194 offset:32768
	ds_read_b128 v[208:211], v194 offset:33792
	ds_read_b128 v[212:215], v194 offset:34816
	ds_read_b128 v[216:219], v194 offset:35840
	ds_read_b128 v[220:223], v194 offset:36864
	ds_read_b128 v[224:227], v194 offset:37888
	ds_read_b128 v[228:231], v194 offset:38912
	ds_read_b128 v[232:235], v194 offset:39936
	global_load_lds_dwordx4 v[238:239], off
	v_lshl_add_u64 v[238:239], s[68:69], 0, v[142:143]
	s_mov_b32 m0, s73
	s_nop 0
	global_load_lds_dwordx4 v[238:239], off
	s_waitcnt vmcnt(8)
	s_waitcnt lgkmcnt(0)
	s_barrier
	s_setprio 1
	v_mfma_f32_16x16x32_bf16 v[124:127], v[128:131], v[204:207], v[124:127]
	v_mfma_f32_16x16x32_bf16 v[120:123], v[136:139], v[204:207], v[120:123]
	v_mfma_f32_16x16x32_bf16 v[96:99], v[128:131], v[212:215], v[96:99]
	v_mfma_f32_16x16x32_bf16 v[88:91], v[136:139], v[212:215], v[88:91]
	v_mfma_f32_16x16x32_bf16 v[76:79], v[128:131], v[220:223], v[76:79]
	v_mfma_f32_16x16x32_bf16 v[72:75], v[136:139], v[220:223], v[72:75]
	v_mfma_f32_16x16x32_bf16 v[60:63], v[128:131], v[228:231], v[60:63]
	v_mfma_f32_16x16x32_bf16 v[108:111], v[136:139], v[228:231], v[108:111]
	v_mfma_f32_16x16x32_bf16 v[124:127], v[132:135], v[208:211], v[124:127]
	v_mfma_f32_16x16x32_bf16 v[120:123], v[158:161], v[208:211], v[120:123]
	v_mfma_f32_16x16x32_bf16 v[96:99], v[132:135], v[216:219], v[96:99]
	v_mfma_f32_16x16x32_bf16 v[88:91], v[158:161], v[216:219], v[88:91]
	v_mfma_f32_16x16x32_bf16 v[76:79], v[132:135], v[224:227], v[76:79]
	v_mfma_f32_16x16x32_bf16 v[72:75], v[158:161], v[224:227], v[72:75]
	v_mfma_f32_16x16x32_bf16 v[60:63], v[132:135], v[232:235], v[60:63]
	v_mfma_f32_16x16x32_bf16 v[108:111], v[158:161], v[232:235], v[108:111]
	s_setprio 0
	s_setprio 1
	v_mfma_f32_16x16x32_bf16 v[116:119], v[168:171], v[204:207], v[116:119]
	v_mfma_f32_16x16x32_bf16 v[112:115], v[196:199], v[204:207], v[112:115]
	v_mfma_f32_16x16x32_bf16 v[84:87], v[168:171], v[212:215], v[84:87]
	v_mfma_f32_16x16x32_bf16 v[80:83], v[196:199], v[212:215], v[80:83]
	v_mfma_f32_16x16x32_bf16 v[68:71], v[168:171], v[220:223], v[68:71]
	v_mfma_f32_16x16x32_bf16 v[64:67], v[196:199], v[220:223], v[64:67]
	v_mfma_f32_16x16x32_bf16 v[104:107], v[168:171], v[228:231], v[104:107]
	v_mfma_f32_16x16x32_bf16 v[56:59], v[196:199], v[228:231], v[56:59]
	v_mfma_f32_16x16x32_bf16 v[116:119], v[172:175], v[208:211], v[116:119]
	v_mfma_f32_16x16x32_bf16 v[112:115], v[200:203], v[208:211], v[112:115]
	v_mfma_f32_16x16x32_bf16 v[84:87], v[172:175], v[216:219], v[84:87]
	v_mfma_f32_16x16x32_bf16 v[80:83], v[200:203], v[216:219], v[80:83]
	v_mfma_f32_16x16x32_bf16 v[68:71], v[172:175], v[224:227], v[68:71]
	v_mfma_f32_16x16x32_bf16 v[64:67], v[200:203], v[224:227], v[64:67]
	v_mfma_f32_16x16x32_bf16 v[104:107], v[172:175], v[232:235], v[104:107]
	v_mfma_f32_16x16x32_bf16 v[56:59], v[200:203], v[232:235], v[56:59]
	s_setprio 0
	s_barrier
	s_add_i32 s68, s87, s23
	v_lshl_add_u64 v[162:163], v[162:163], 0, s[36:37]
	s_mov_b32 m0, s68
	ds_read_b128 v[204:207], v194 offset:49152
	ds_read_b128 v[208:211], v194 offset:50176
	ds_read_b128 v[212:215], v194 offset:51200
	ds_read_b128 v[216:219], v194 offset:52224
	ds_read_b128 v[220:223], v194 offset:53248
	ds_read_b128 v[224:227], v194 offset:54272
	ds_read_b128 v[228:231], v194 offset:55296
	ds_read_b128 v[232:235], v194 offset:56320
	global_load_lds_dwordx4 v[162:163], off
	s_add_i32 m0, s68, 0x2000
	s_add_u32 s66, s66, 0x40080
	v_lshl_add_u64 v[162:163], v[178:179], 0, s[36:37]
	s_addc_u32 s67, s67, 0
	s_add_i32 s68, s88, s23
	global_load_lds_dwordx4 v[162:163], off
	v_lshl_add_u64 v[162:163], s[66:67], 0, v[140:141]
	s_mov_b32 m0, s68
	s_nop 0
	global_load_lds_dwordx4 v[162:163], off
	v_lshl_add_u64 v[162:163], s[66:67], 0, v[142:143]
	s_add_i32 m0, s68, 0x2000
	s_nop 0
	global_load_lds_dwordx4 v[162:163], off
	v_lshl_add_u64 v[162:163], v[184:185], 0, s[36:37]
	s_mov_b32 m0, s80
	s_nop 0
	global_load_lds_dwordx4 v[162:163], off
	v_lshl_add_u64 v[162:163], v[236:237], 0, s[36:37]
	s_mov_b32 m0, s81
	s_nop 0
	global_load_lds_dwordx4 v[162:163], off
	s_waitcnt vmcnt(8)
	s_waitcnt lgkmcnt(0)
	s_barrier
	s_setprio 1
	v_mfma_f32_16x16x32_bf16 v[52:55], v[128:131], v[204:207], v[52:55]
	v_mfma_f32_16x16x32_bf16 v[48:51], v[136:139], v[204:207], v[48:51]
	v_mfma_f32_16x16x32_bf16 v[16:19], v[128:131], v[212:215], v[16:19]
	v_mfma_f32_16x16x32_bf16 v[8:11], v[136:139], v[212:215], v[8:11]
	v_mfma_f32_16x16x32_bf16 v[28:31], v[128:131], v[220:223], v[28:31]
	v_mfma_f32_16x16x32_bf16 v[24:27], v[136:139], v[220:223], v[24:27]
	v_mfma_f32_16x16x32_bf16 v[36:39], v[128:131], v[228:231], v[36:39]
	v_mfma_f32_16x16x32_bf16 v[100:103], v[136:139], v[228:231], v[100:103]
	v_mfma_f32_16x16x32_bf16 v[52:55], v[132:135], v[208:211], v[52:55]
	v_mfma_f32_16x16x32_bf16 v[48:51], v[158:161], v[208:211], v[48:51]
	v_mfma_f32_16x16x32_bf16 v[16:19], v[132:135], v[216:219], v[16:19]
	v_mfma_f32_16x16x32_bf16 v[8:11], v[158:161], v[216:219], v[8:11]
	v_mfma_f32_16x16x32_bf16 v[28:31], v[132:135], v[224:227], v[28:31]
	v_mfma_f32_16x16x32_bf16 v[24:27], v[158:161], v[224:227], v[24:27]
	v_mfma_f32_16x16x32_bf16 v[36:39], v[132:135], v[232:235], v[36:39]
	v_mfma_f32_16x16x32_bf16 v[100:103], v[158:161], v[232:235], v[100:103]
	s_setprio 0
	s_setprio 1
	v_mfma_f32_16x16x32_bf16 v[44:47], v[168:171], v[204:207], v[44:47]
	v_mfma_f32_16x16x32_bf16 v[40:43], v[196:199], v[204:207], v[40:43]
	v_mfma_f32_16x16x32_bf16 v[0:3], v[168:171], v[212:215], v[0:3]
	v_mfma_f32_16x16x32_bf16 v[4:7], v[196:199], v[212:215], v[4:7]
	v_mfma_f32_16x16x32_bf16 v[12:15], v[168:171], v[220:223], v[12:15]
	v_mfma_f32_16x16x32_bf16 v[20:23], v[196:199], v[220:223], v[20:23]
	v_mfma_f32_16x16x32_bf16 v[92:95], v[168:171], v[228:231], v[92:95]
	v_mfma_f32_16x16x32_bf16 v[32:35], v[196:199], v[228:231], v[32:35]
	v_mfma_f32_16x16x32_bf16 v[44:47], v[172:175], v[208:211], v[44:47]
	v_mfma_f32_16x16x32_bf16 v[40:43], v[200:203], v[208:211], v[40:43]
	v_mfma_f32_16x16x32_bf16 v[0:3], v[172:175], v[216:219], v[0:3]
	v_mfma_f32_16x16x32_bf16 v[4:7], v[200:203], v[216:219], v[4:7]
	v_mfma_f32_16x16x32_bf16 v[12:15], v[172:175], v[224:227], v[12:15]
	v_mfma_f32_16x16x32_bf16 v[20:23], v[200:203], v[224:227], v[20:23]
	v_mfma_f32_16x16x32_bf16 v[92:95], v[172:175], v[232:235], v[92:95]
	v_mfma_f32_16x16x32_bf16 v[32:35], v[200:203], v[232:235], v[32:35]
	s_setprio 0
	s_barrier
	s_add_i32 s86, s86, 2
	s_add_u32 s64, s64, 0x100
	s_addc_u32 s65, s65, 0
	s_add_u32 s84, s84, 0x100
	s_addc_u32 s85, s85, 0
	s_cmp_gt_u32 s86, 13
	s_cbranch_scc0 .LBB0_439
	s_and_b64 vcc, exec, s[38:39]
	s_cbranch_vccz .LBB0_442
	s_barrier
.LBB0_442:
	s_lshl_b32 s55, s52, 8
	v_add_u32_e32 v184, s55, v165
	v_mbcnt_lo_u32_b32 v128, -1, 0
	v_mbcnt_hi_u32_b32 v128, -1, v128
	v_ashrrev_i32_e32 v185, 31, v184
	v_lshl_add_u64 v[128:129], v[184:185], 2, s[20:21]
	v_add_u32_e32 v158, 0xb0, v184
	v_add_u32_e32 v170, 0x80, v184
	v_add_u32_e32 v162, 0x90, v184
	v_add_u32_e32 v160, 0xa0, v184
	v_ashrrev_i32_e32 v159, 31, v158
	v_ashrrev_i32_e32 v171, 31, v170
	v_ashrrev_i32_e32 v163, 31, v162
	v_ashrrev_i32_e32 v161, 31, v160
	v_lshl_add_u64 v[136:137], v[158:159], 2, s[20:21]
	v_lshl_add_u64 v[130:131], v[170:171], 2, s[20:21]
	v_lshl_add_u64 v[132:133], v[162:163], 2, s[20:21]
	v_lshl_add_u64 v[134:135], v[160:161], 2, s[20:21]
	s_waitcnt vmcnt(14)
	v_mov_b32_e32 v178, v245
	v_mov_b32_e32 v168, v250
	v_mov_b32_e32 v186, v242
	v_mov_b32_e32 v182, v243
	v_mov_b32_e32 v180, v244
	v_mov_b32_e32 v176, v246
	v_mov_b32_e32 v164, v248
	v_mov_b32_e32 v166, v249
	v_pk_mul_f32 v[108:109], v[108:109], v[178:179] op_sel_hi:[1,0]
	v_pk_mul_f32 v[110:111], v[110:111], v[178:179] op_sel_hi:[1,0]
	v_pk_mul_f32 v[104:105], v[104:105], v[178:179] op_sel_hi:[1,0]
	v_pk_mul_f32 v[106:107], v[106:107], v[178:179] op_sel_hi:[1,0]
	v_pk_mul_f32 v[128:129], v[108:109], v[104:105]
	v_pk_mul_f32 v[130:131], v[110:111], v[106:107]
	v_pk_mul_f32 v[100:101], v[100:101], v[168:169] op_sel_hi:[1,0]
	v_pk_mul_f32 v[102:103], v[102:103], v[168:169] op_sel_hi:[1,0]
	v_pk_mul_f32 v[92:93], v[92:93], v[168:169] op_sel_hi:[1,0]
	v_pk_mul_f32 v[94:95], v[94:95], v[168:169] op_sel_hi:[1,0]
	v_pk_mul_f32 v[92:93], v[100:101], v[92:93]
	v_pk_mul_f32 v[94:95], v[102:103], v[94:95]
	s_and_saveexec_b64 s[64:65], s[4:5]
	s_cbranch_execz .LBB0_444
	ds_write_b128 v195, v[128:131]
	ds_write_b128 v195, v[92:95] offset:1024

.LBB0_504:
	ds_read_b128 v[104:107], v200
	ds_read_b128 v[108:111], v200 offset:1024
	ds_read_b128 v[124:127], v200 offset:2048
	ds_read_b128 v[128:131], v200 offset:3072
	ds_read_b128 v[144:147], v201
	ds_read_b128 v[148:151], v201 offset:1024
	ds_read_b128 v[152:155], v201 offset:2048
	ds_read_b128 v[156:159], v201 offset:3072
	s_add_u32 s48, s46, 0xfffc0080
	s_addc_u32 s49, s47, -1
	s_cmp_eq_u32 s87, 12
	s_cselect_b32 s51, s39, s49
	s_cselect_b32 s50, s45, s48
	s_cselect_b32 s49, s37, s86
	s_cselect_b32 s48, s84, s85
	v_lshl_add_u64 v[196:197], s[46:47], 0, v[188:189]
	s_add_i32 m0, s52, 0xc000
	ds_read_b128 v[160:163], v202
	ds_read_b128 v[164:167], v202 offset:1024
	ds_read_b128 v[168:171], v202 offset:2048
	ds_read_b128 v[172:175], v202 offset:3072
	ds_read_b128 v[176:179], v202 offset:4096
	ds_read_b128 v[180:183], v202 offset:5120
	ds_read_b128 v[206:209], v202 offset:6144
	ds_read_b128 v[210:213], v202 offset:7168
	global_load_lds_dwordx4 v[196:197], off
	v_lshl_add_u64 v[196:197], s[46:47], 0, v[190:191]
	s_add_i32 m0, s52, 0xe000
	s_nop 0
	global_load_lds_dwordx4 v[196:197], off
	s_waitcnt vmcnt(8)
	s_waitcnt lgkmcnt(0)
	s_barrier
	s_setprio 1
	v_mfma_f32_16x16x32_bf16 v[140:143], v[104:107], v[160:163], v[140:143]
	v_mfma_f32_16x16x32_bf16 v[136:139], v[124:127], v[160:163], v[136:139]
	v_mfma_f32_16x16x32_bf16 v[116:119], v[104:107], v[168:171], v[116:119]
	v_mfma_f32_16x16x32_bf16 v[112:115], v[124:127], v[168:171], v[112:115]
	v_mfma_f32_16x16x32_bf16 v[92:95], v[104:107], v[176:179], v[92:95]
	v_mfma_f32_16x16x32_bf16 v[88:91], v[124:127], v[176:179], v[88:91]
	v_mfma_f32_16x16x32_bf16 v[76:79], v[104:107], v[206:209], v[76:79]
	v_mfma_f32_16x16x32_bf16 v[72:75], v[124:127], v[206:209], v[72:75]
	v_mfma_f32_16x16x32_bf16 v[140:143], v[108:111], v[164:167], v[140:143]
	v_mfma_f32_16x16x32_bf16 v[136:139], v[128:131], v[164:167], v[136:139]
	v_mfma_f32_16x16x32_bf16 v[116:119], v[108:111], v[172:175], v[116:119]
	v_mfma_f32_16x16x32_bf16 v[112:115], v[128:131], v[172:175], v[112:115]
	v_mfma_f32_16x16x32_bf16 v[92:95], v[108:111], v[180:183], v[92:95]
	v_mfma_f32_16x16x32_bf16 v[88:91], v[128:131], v[180:183], v[88:91]
	v_mfma_f32_16x16x32_bf16 v[76:79], v[108:111], v[210:213], v[76:79]
	v_mfma_f32_16x16x32_bf16 v[72:75], v[128:131], v[210:213], v[72:75]
	s_setprio 0
	s_setprio 1
	v_mfma_f32_16x16x32_bf16 v[132:135], v[144:147], v[160:163], v[132:135]
	v_mfma_f32_16x16x32_bf16 v[120:123], v[152:155], v[160:163], v[120:123]
	v_mfma_f32_16x16x32_bf16 v[100:103], v[144:147], v[168:171], v[100:103]
	v_mfma_f32_16x16x32_bf16 v[96:99], v[152:155], v[168:171], v[96:99]
	v_mfma_f32_16x16x32_bf16 v[84:87], v[144:147], v[176:179], v[84:87]
	v_mfma_f32_16x16x32_bf16 v[80:83], v[152:155], v[176:179], v[80:83]
	v_mfma_f32_16x16x32_bf16 v[68:71], v[144:147], v[206:209], v[68:71]
	v_mfma_f32_16x16x32_bf16 v[64:67], v[152:155], v[206:209], v[64:67]
	v_mfma_f32_16x16x32_bf16 v[132:135], v[148:151], v[164:167], v[132:135]
	v_mfma_f32_16x16x32_bf16 v[120:123], v[156:159], v[164:167], v[120:123]
	v_mfma_f32_16x16x32_bf16 v[100:103], v[148:151], v[172:175], v[100:103]
	v_mfma_f32_16x16x32_bf16 v[96:99], v[156:159], v[172:175], v[96:99]
	v_mfma_f32_16x16x32_bf16 v[84:87], v[148:151], v[180:183], v[84:87]
	v_mfma_f32_16x16x32_bf16 v[80:83], v[156:159], v[180:183], v[80:83]
	v_mfma_f32_16x16x32_bf16 v[68:71], v[148:151], v[210:213], v[68:71]
	v_mfma_f32_16x16x32_bf16 v[64:67], v[156:159], v[210:213], v[64:67]
	s_setprio 0
	s_barrier
	s_add_i32 s88, s69, s13
	v_lshl_add_u64 v[196:197], s[48:49], 0, v[184:185]
	s_mov_b32 m0, s88
	ds_read_b128 v[160:163], v202 offset:16384
	ds_read_b128 v[164:167], v202 offset:17408
	ds_read_b128 v[168:171], v202 offset:18432
	ds_read_b128 v[172:175], v202 offset:19456
	ds_read_b128 v[176:179], v202 offset:20480
	ds_read_b128 v[180:183], v202 offset:21504
	ds_read_b128 v[206:209], v202 offset:22528
	ds_read_b128 v[210:213], v202 offset:23552
	global_load_lds_dwordx4 v[196:197], off
	s_add_i32 m0, s88, 0x2000
	s_add_u32 s88, s48, 0x40000
	v_lshl_add_u64 v[214:215], s[48:49], 0, v[186:187]
	s_addc_u32 s89, s49, 0
	s_add_i32 s90, s70, s13
	global_load_lds_dwordx4 v[214:215], off
	v_lshl_add_u64 v[216:217], s[88:89], 0, v[184:185]
	s_mov_b32 m0, s90
	v_lshl_add_u64 v[218:219], s[50:51], 0, v[186:187]
	global_load_lds_dwordx4 v[216:217], off
	v_lshl_add_u64 v[216:217], s[88:89], 0, v[186:187]
	s_add_i32 m0, s90, 0x2000
	s_nop 0
	global_load_lds_dwordx4 v[216:217], off
	v_lshl_add_u64 v[216:217], s[50:51], 0, v[184:185]
	s_mov_b32 m0, s52
	s_nop 0
	global_load_lds_dwordx4 v[216:217], off
	s_mov_b32 m0, s53
	s_nop 0
	global_load_lds_dwordx4 v[218:219], off
	s_waitcnt vmcnt(8)
	s_waitcnt lgkmcnt(0)
	s_barrier
	s_setprio 1
	v_mfma_f32_16x16x32_bf16 v[60:63], v[104:107], v[160:163], v[60:63]
	v_mfma_f32_16x16x32_bf16 v[56:59], v[124:127], v[160:163], v[56:59]
	v_mfma_f32_16x16x32_bf16 v[44:47], v[104:107], v[168:171], v[44:47]
	v_mfma_f32_16x16x32_bf16 v[40:43], v[124:127], v[168:171], v[40:43]
	v_mfma_f32_16x16x32_bf16 v[28:31], v[104:107], v[176:179], v[28:31]
	v_mfma_f32_16x16x32_bf16 v[24:27], v[124:127], v[176:179], v[24:27]
	v_mfma_f32_16x16x32_bf16 v[12:15], v[104:107], v[206:209], v[12:15]
	v_mfma_f32_16x16x32_bf16 v[8:11], v[124:127], v[206:209], v[8:11]
	v_mfma_f32_16x16x32_bf16 v[60:63], v[108:111], v[164:167], v[60:63]
	v_mfma_f32_16x16x32_bf16 v[56:59], v[128:131], v[164:167], v[56:59]
	v_mfma_f32_16x16x32_bf16 v[44:47], v[108:111], v[172:175], v[44:47]
	v_mfma_f32_16x16x32_bf16 v[40:43], v[128:131], v[172:175], v[40:43]
	v_mfma_f32_16x16x32_bf16 v[28:31], v[108:111], v[180:183], v[28:31]
	v_mfma_f32_16x16x32_bf16 v[24:27], v[128:131], v[180:183], v[24:27]
	v_mfma_f32_16x16x32_bf16 v[12:15], v[108:111], v[210:213], v[12:15]
	v_mfma_f32_16x16x32_bf16 v[8:11], v[128:131], v[210:213], v[8:11]
	s_setprio 0
	s_setprio 1
	v_mfma_f32_16x16x32_bf16 v[52:55], v[144:147], v[160:163], v[52:55]
	v_mfma_f32_16x16x32_bf16 v[48:51], v[152:155], v[160:163], v[48:51]
	v_mfma_f32_16x16x32_bf16 v[36:39], v[144:147], v[168:171], v[36:39]
	v_mfma_f32_16x16x32_bf16 v[32:35], v[152:155], v[168:171], v[32:35]
	v_mfma_f32_16x16x32_bf16 v[20:23], v[144:147], v[176:179], v[20:23]
	v_mfma_f32_16x16x32_bf16 v[16:19], v[152:155], v[176:179], v[16:19]
	v_mfma_f32_16x16x32_bf16 v[4:7], v[144:147], v[206:209], v[4:7]
	v_mfma_f32_16x16x32_bf16 v[0:3], v[152:155], v[206:209], v[0:3]
	v_mfma_f32_16x16x32_bf16 v[52:55], v[148:151], v[164:167], v[52:55]
	v_mfma_f32_16x16x32_bf16 v[48:51], v[156:159], v[164:167], v[48:51]
	v_mfma_f32_16x16x32_bf16 v[36:39], v[148:151], v[172:175], v[36:39]
	v_mfma_f32_16x16x32_bf16 v[32:35], v[156:159], v[172:175], v[32:35]
	v_mfma_f32_16x16x32_bf16 v[20:23], v[148:151], v[180:183], v[20:23]
	v_mfma_f32_16x16x32_bf16 v[16:19], v[156:159], v[180:183], v[16:19]
	v_mfma_f32_16x16x32_bf16 v[4:7], v[148:151], v[210:213], v[4:7]
	v_mfma_f32_16x16x32_bf16 v[0:3], v[156:159], v[210:213], v[0:3]
	s_setprio 0
	s_barrier
	s_add_i32 s88, 0, 0x18000
	s_add_i32 s89, 0, 0x1c000
	v_add_u32_e32 v128, s88, v199
	v_add_u32_e32 v156, s89, v199
	ds_read_b128 v[104:107], v128
	ds_read_b128 v[108:111], v128 offset:1024
	ds_read_b128 v[124:127], v128 offset:2048
	ds_read_b128 v[128:131], v128 offset:3072
	ds_read_b128 v[144:147], v156
	ds_read_b128 v[148:151], v156 offset:1024
	ds_read_b128 v[152:155], v156 offset:2048
	ds_read_b128 v[156:159], v156 offset:3072
	s_add_u32 s50, s50, 0x40000
	s_addc_u32 s51, s51, 0
	s_mov_b32 m0, s54
	v_lshl_add_u64 v[220:221], s[50:51], 0, v[184:185]
	ds_read_b128 v[160:163], v202 offset:32768
	ds_read_b128 v[164:167], v202 offset:33792
	ds_read_b128 v[168:171], v202 offset:34816
	ds_read_b128 v[172:175], v202 offset:35840
	ds_read_b128 v[176:179], v202 offset:36864
	ds_read_b128 v[180:183], v202 offset:37888
	ds_read_b128 v[206:209], v202 offset:38912
	ds_read_b128 v[210:213], v202 offset:39936
	global_load_lds_dwordx4 v[220:221], off
	v_lshl_add_u64 v[220:221], s[50:51], 0, v[186:187]
	s_mov_b32 m0, s55
	s_nop 0
	global_load_lds_dwordx4 v[220:221], off
	s_waitcnt vmcnt(8)
	s_waitcnt lgkmcnt(0)
	s_barrier
	s_setprio 1
	v_mfma_f32_16x16x32_bf16 v[140:143], v[104:107], v[160:163], v[140:143]
	v_mfma_f32_16x16x32_bf16 v[136:139], v[124:127], v[160:163], v[136:139]
	v_mfma_f32_16x16x32_bf16 v[116:119], v[104:107], v[168:171], v[116:119]
	v_mfma_f32_16x16x32_bf16 v[112:115], v[124:127], v[168:171], v[112:115]
	v_mfma_f32_16x16x32_bf16 v[92:95], v[104:107], v[176:179], v[92:95]
	v_mfma_f32_16x16x32_bf16 v[88:91], v[124:127], v[176:179], v[88:91]
	v_mfma_f32_16x16x32_bf16 v[76:79], v[104:107], v[206:209], v[76:79]
	v_mfma_f32_16x16x32_bf16 v[72:75], v[124:127], v[206:209], v[72:75]
	v_mfma_f32_16x16x32_bf16 v[140:143], v[108:111], v[164:167], v[140:143]
	v_mfma_f32_16x16x32_bf16 v[136:139], v[128:131], v[164:167], v[136:139]
	v_mfma_f32_16x16x32_bf16 v[116:119], v[108:111], v[172:175], v[116:119]
	v_mfma_f32_16x16x32_bf16 v[112:115], v[128:131], v[172:175], v[112:115]
	v_mfma_f32_16x16x32_bf16 v[92:95], v[108:111], v[180:183], v[92:95]
	v_mfma_f32_16x16x32_bf16 v[88:91], v[128:131], v[180:183], v[88:91]
	v_mfma_f32_16x16x32_bf16 v[76:79], v[108:111], v[210:213], v[76:79]
	v_mfma_f32_16x16x32_bf16 v[72:75], v[128:131], v[210:213], v[72:75]
	s_setprio 0
	s_setprio 1
	v_mfma_f32_16x16x32_bf16 v[132:135], v[144:147], v[160:163], v[132:135]
	v_mfma_f32_16x16x32_bf16 v[120:123], v[152:155], v[160:163], v[120:123]
	v_mfma_f32_16x16x32_bf16 v[100:103], v[144:147], v[168:171], v[100:103]
	v_mfma_f32_16x16x32_bf16 v[96:99], v[152:155], v[168:171], v[96:99]
	v_mfma_f32_16x16x32_bf16 v[84:87], v[144:147], v[176:179], v[84:87]
	v_mfma_f32_16x16x32_bf16 v[80:83], v[152:155], v[176:179], v[80:83]
	v_mfma_f32_16x16x32_bf16 v[68:71], v[144:147], v[206:209], v[68:71]
	v_mfma_f32_16x16x32_bf16 v[64:67], v[152:155], v[206:209], v[64:67]
	v_mfma_f32_16x16x32_bf16 v[132:135], v[148:151], v[164:167], v[132:135]
	v_mfma_f32_16x16x32_bf16 v[120:123], v[156:159], v[164:167], v[120:123]
	v_mfma_f32_16x16x32_bf16 v[100:103], v[148:151], v[172:175], v[100:103]
	v_mfma_f32_16x16x32_bf16 v[96:99], v[156:159], v[172:175], v[96:99]
	v_mfma_f32_16x16x32_bf16 v[84:87], v[148:151], v[180:183], v[84:87]
	v_mfma_f32_16x16x32_bf16 v[80:83], v[156:159], v[180:183], v[80:83]
	v_mfma_f32_16x16x32_bf16 v[68:71], v[148:151], v[210:213], v[68:71]
	v_mfma_f32_16x16x32_bf16 v[64:67], v[156:159], v[210:213], v[64:67]
	s_setprio 0
	s_barrier
	s_add_i32 s50, s88, s13
	v_lshl_add_u64 v[196:197], v[196:197], 0, s[30:31]
	s_mov_b32 m0, s50
	ds_read_b128 v[160:163], v202 offset:49152
	ds_read_b128 v[164:167], v202 offset:50176
	ds_read_b128 v[168:171], v202 offset:51200
	ds_read_b128 v[172:175], v202 offset:52224
	ds_read_b128 v[176:179], v202 offset:53248
	ds_read_b128 v[180:183], v202 offset:54272
	ds_read_b128 v[206:209], v202 offset:55296
	ds_read_b128 v[210:213], v202 offset:56320
	global_load_lds_dwordx4 v[196:197], off
	s_add_i32 m0, s50, 0x2000
	s_add_u32 s48, s48, 0x40080
	v_lshl_add_u64 v[196:197], v[214:215], 0, s[30:31]
	s_addc_u32 s49, s49, 0
	s_add_i32 s50, s89, s13
	global_load_lds_dwordx4 v[196:197], off
	v_lshl_add_u64 v[196:197], s[48:49], 0, v[184:185]
	s_mov_b32 m0, s50
	s_nop 0
	global_load_lds_dwordx4 v[196:197], off
	v_lshl_add_u64 v[196:197], s[48:49], 0, v[186:187]
	s_add_i32 m0, s50, 0x2000
	s_nop 0
	global_load_lds_dwordx4 v[196:197], off
	v_lshl_add_u64 v[196:197], v[216:217], 0, s[30:31]
	s_mov_b32 m0, s61
	s_nop 0
	global_load_lds_dwordx4 v[196:197], off
	v_lshl_add_u64 v[196:197], v[218:219], 0, s[30:31]
	s_mov_b32 m0, s62
	s_nop 0
	global_load_lds_dwordx4 v[196:197], off
	s_waitcnt vmcnt(8)
	s_waitcnt lgkmcnt(0)
	s_barrier
	s_setprio 1
	v_mfma_f32_16x16x32_bf16 v[60:63], v[104:107], v[160:163], v[60:63]
	v_mfma_f32_16x16x32_bf16 v[56:59], v[124:127], v[160:163], v[56:59]
	v_mfma_f32_16x16x32_bf16 v[44:47], v[104:107], v[168:171], v[44:47]
	v_mfma_f32_16x16x32_bf16 v[40:43], v[124:127], v[168:171], v[40:43]
	v_mfma_f32_16x16x32_bf16 v[28:31], v[104:107], v[176:179], v[28:31]
	v_mfma_f32_16x16x32_bf16 v[24:27], v[124:127], v[176:179], v[24:27]
	v_mfma_f32_16x16x32_bf16 v[12:15], v[104:107], v[206:209], v[12:15]
	v_mfma_f32_16x16x32_bf16 v[8:11], v[124:127], v[206:209], v[8:11]
	v_mfma_f32_16x16x32_bf16 v[60:63], v[108:111], v[164:167], v[60:63]
	v_mfma_f32_16x16x32_bf16 v[56:59], v[128:131], v[164:167], v[56:59]
	v_mfma_f32_16x16x32_bf16 v[44:47], v[108:111], v[172:175], v[44:47]
	v_mfma_f32_16x16x32_bf16 v[40:43], v[128:131], v[172:175], v[40:43]
	v_mfma_f32_16x16x32_bf16 v[28:31], v[108:111], v[180:183], v[28:31]
	v_mfma_f32_16x16x32_bf16 v[24:27], v[128:131], v[180:183], v[24:27]
	v_mfma_f32_16x16x32_bf16 v[12:15], v[108:111], v[210:213], v[12:15]
	v_mfma_f32_16x16x32_bf16 v[8:11], v[128:131], v[210:213], v[8:11]
	s_setprio 0
	s_setprio 1
	v_mfma_f32_16x16x32_bf16 v[52:55], v[144:147], v[160:163], v[52:55]
	v_mfma_f32_16x16x32_bf16 v[48:51], v[152:155], v[160:163], v[48:51]
	v_mfma_f32_16x16x32_bf16 v[36:39], v[144:147], v[168:171], v[36:39]
	v_mfma_f32_16x16x32_bf16 v[32:35], v[152:155], v[168:171], v[32:35]
	v_mfma_f32_16x16x32_bf16 v[20:23], v[144:147], v[176:179], v[20:23]
	v_mfma_f32_16x16x32_bf16 v[16:19], v[152:155], v[176:179], v[16:19]
	v_mfma_f32_16x16x32_bf16 v[4:7], v[144:147], v[206:209], v[4:7]
	v_mfma_f32_16x16x32_bf16 v[0:3], v[152:155], v[206:209], v[0:3]
	v_mfma_f32_16x16x32_bf16 v[52:55], v[148:151], v[164:167], v[52:55]
	v_mfma_f32_16x16x32_bf16 v[48:51], v[156:159], v[164:167], v[48:51]
	v_mfma_f32_16x16x32_bf16 v[36:39], v[148:151], v[172:175], v[36:39]
	v_mfma_f32_16x16x32_bf16 v[32:35], v[156:159], v[172:175], v[32:35]
	v_mfma_f32_16x16x32_bf16 v[20:23], v[148:151], v[180:183], v[20:23]
	v_mfma_f32_16x16x32_bf16 v[16:19], v[156:159], v[180:183], v[16:19]
	v_mfma_f32_16x16x32_bf16 v[4:7], v[148:151], v[210:213], v[4:7]
	v_mfma_f32_16x16x32_bf16 v[0:3], v[156:159], v[210:213], v[0:3]
	s_setprio 0
	s_barrier
	s_add_i32 s87, s87, 2
	s_add_u32 s46, s46, 0x100
	s_addc_u32 s47, s47, 0
	s_add_u32 s85, s85, 0x100
	s_addc_u32 s86, s86, 0
	s_cmp_gt_u32 s87, 13
	s_cbranch_scc0 .LBB0_504
	s_and_b64 vcc, exec, s[34:35]
	s_cbranch_vccz .LBB0_507
	s_barrier

.LBB0_552:
	ds_read_b128 v[128:131], v173
	ds_read_b128 v[132:135], v173 offset:1024
	ds_read_b128 v[136:139], v173 offset:2048
	ds_read_b128 v[140:143], v173 offset:3072
	ds_read_b128 v[160:163], v179
	ds_read_b128 v[174:177], v179 offset:1024
	ds_read_b128 v[194:197], v179 offset:2048
	ds_read_b128 v[198:201], v179 offset:3072
	s_add_u32 s57, s62, 0xfffc0080
	s_addc_u32 s64, s63, -1
	s_cmp_eq_u32 s55, 12
	s_cselect_b32 s67, s9, s64
	s_cselect_b32 s66, s11, s57
	s_cselect_b32 s65, s13, s23
	s_cselect_b32 s64, s16, s22
	v_lshl_add_u64 v[166:167], s[62:63], 0, v[152:153]
	s_add_i32 m0, s86, 0xc000
	ds_read_b128 v[202:205], v183
	ds_read_b128 v[206:209], v183 offset:1024
	ds_read_b128 v[210:213], v183 offset:2048
	ds_read_b128 v[214:217], v183 offset:3072
	ds_read_b128 v[218:221], v183 offset:4096
	ds_read_b128 v[222:225], v183 offset:5120
	ds_read_b128 v[226:229], v183 offset:6144
	ds_read_b128 v[230:233], v183 offset:7168
	global_load_lds_dwordx4 v[166:167], off
	v_lshl_add_u64 v[166:167], s[62:63], 0, v[154:155]
	s_add_i32 m0, s86, 0xe000
	s_nop 0
	global_load_lds_dwordx4 v[166:167], off
	s_waitcnt vmcnt(8)
	s_waitcnt lgkmcnt(0)
	s_barrier
	s_setprio 1
	v_mfma_f32_16x16x32_bf16 v[124:127], v[128:131], v[202:205], v[124:127]
	v_mfma_f32_16x16x32_bf16 v[120:123], v[136:139], v[202:205], v[120:123]
	v_mfma_f32_16x16x32_bf16 v[108:111], v[128:131], v[210:213], v[108:111]
	v_mfma_f32_16x16x32_bf16 v[104:107], v[136:139], v[210:213], v[104:107]
	v_mfma_f32_16x16x32_bf16 v[92:95], v[128:131], v[218:221], v[92:95]
	v_mfma_f32_16x16x32_bf16 v[88:91], v[136:139], v[218:221], v[88:91]
	v_mfma_f32_16x16x32_bf16 v[76:79], v[128:131], v[226:229], v[76:79]
	v_mfma_f32_16x16x32_bf16 v[72:75], v[136:139], v[226:229], v[72:75]
	v_mfma_f32_16x16x32_bf16 v[124:127], v[132:135], v[206:209], v[124:127]
	v_mfma_f32_16x16x32_bf16 v[120:123], v[140:143], v[206:209], v[120:123]
	v_mfma_f32_16x16x32_bf16 v[108:111], v[132:135], v[214:217], v[108:111]
	v_mfma_f32_16x16x32_bf16 v[104:107], v[140:143], v[214:217], v[104:107]
	v_mfma_f32_16x16x32_bf16 v[92:95], v[132:135], v[222:225], v[92:95]
	v_mfma_f32_16x16x32_bf16 v[88:91], v[140:143], v[222:225], v[88:91]
	v_mfma_f32_16x16x32_bf16 v[76:79], v[132:135], v[230:233], v[76:79]
	v_mfma_f32_16x16x32_bf16 v[72:75], v[140:143], v[230:233], v[72:75]
	s_setprio 0
	s_setprio 1
	v_mfma_f32_16x16x32_bf16 v[116:119], v[160:163], v[202:205], v[116:119]
	v_mfma_f32_16x16x32_bf16 v[112:115], v[194:197], v[202:205], v[112:115]
	v_mfma_f32_16x16x32_bf16 v[100:103], v[160:163], v[210:213], v[100:103]
	v_mfma_f32_16x16x32_bf16 v[96:99], v[194:197], v[210:213], v[96:99]
	v_mfma_f32_16x16x32_bf16 v[84:87], v[160:163], v[218:221], v[84:87]
	v_mfma_f32_16x16x32_bf16 v[80:83], v[194:197], v[218:221], v[80:83]
	v_mfma_f32_16x16x32_bf16 v[68:71], v[160:163], v[226:229], v[68:71]
	v_mfma_f32_16x16x32_bf16 v[64:67], v[194:197], v[226:229], v[64:67]
	v_mfma_f32_16x16x32_bf16 v[116:119], v[174:177], v[206:209], v[116:119]
	v_mfma_f32_16x16x32_bf16 v[112:115], v[198:201], v[206:209], v[112:115]
	v_mfma_f32_16x16x32_bf16 v[100:103], v[174:177], v[214:217], v[100:103]
	v_mfma_f32_16x16x32_bf16 v[96:99], v[198:201], v[214:217], v[96:99]
	v_mfma_f32_16x16x32_bf16 v[84:87], v[174:177], v[222:225], v[84:87]
	v_mfma_f32_16x16x32_bf16 v[80:83], v[198:201], v[222:225], v[80:83]
	v_mfma_f32_16x16x32_bf16 v[68:71], v[174:177], v[230:233], v[68:71]
	v_mfma_f32_16x16x32_bf16 v[64:67], v[198:201], v[230:233], v[64:67]
	s_setprio 0
	s_barrier
	s_add_i32 s57, s0, s85
	v_lshl_add_u64 v[166:167], s[64:65], 0, v[144:145]
	s_mov_b32 m0, s57
	ds_read_b128 v[202:205], v183 offset:16384
	ds_read_b128 v[206:209], v183 offset:17408
	ds_read_b128 v[210:213], v183 offset:18432
	ds_read_b128 v[214:217], v183 offset:19456
	ds_read_b128 v[218:221], v183 offset:20480
	ds_read_b128 v[222:225], v183 offset:21504
	ds_read_b128 v[226:229], v183 offset:22528
	ds_read_b128 v[230:233], v183 offset:23552
	global_load_lds_dwordx4 v[166:167], off
	s_add_i32 m0, s57, 0x2000
	s_add_u32 s68, s64, 0x40000
	v_lshl_add_u64 v[170:171], s[64:65], 0, v[146:147]
	s_addc_u32 s69, s65, 0
	s_add_i32 s57, s1, s85
	global_load_lds_dwordx4 v[170:171], off
	v_lshl_add_u64 v[180:181], s[68:69], 0, v[144:145]
	s_mov_b32 m0, s57
	v_lshl_add_u64 v[184:185], s[66:67], 0, v[146:147]
	global_load_lds_dwordx4 v[180:181], off
	v_lshl_add_u64 v[180:181], s[68:69], 0, v[146:147]
	s_add_i32 m0, s57, 0x2000
	s_nop 0
	global_load_lds_dwordx4 v[180:181], off
	v_lshl_add_u64 v[180:181], s[66:67], 0, v[144:145]
	s_mov_b32 m0, s86
	s_nop 0
	global_load_lds_dwordx4 v[180:181], off
	s_mov_b32 m0, s87
	s_nop 0
	global_load_lds_dwordx4 v[184:185], off
	s_waitcnt vmcnt(8)
	s_waitcnt lgkmcnt(0)
	s_barrier
	s_setprio 1
	v_mfma_f32_16x16x32_bf16 v[60:63], v[128:131], v[202:205], v[60:63]
	v_mfma_f32_16x16x32_bf16 v[56:59], v[136:139], v[202:205], v[56:59]
	v_mfma_f32_16x16x32_bf16 v[44:47], v[128:131], v[210:213], v[44:47]
	v_mfma_f32_16x16x32_bf16 v[40:43], v[136:139], v[210:213], v[40:43]
	v_mfma_f32_16x16x32_bf16 v[28:31], v[128:131], v[218:221], v[28:31]
	v_mfma_f32_16x16x32_bf16 v[24:27], v[136:139], v[218:221], v[24:27]
	v_mfma_f32_16x16x32_bf16 v[12:15], v[128:131], v[226:229], v[12:15]
	v_mfma_f32_16x16x32_bf16 v[8:11], v[136:139], v[226:229], v[8:11]
	v_mfma_f32_16x16x32_bf16 v[60:63], v[132:135], v[206:209], v[60:63]
	v_mfma_f32_16x16x32_bf16 v[56:59], v[140:143], v[206:209], v[56:59]
	v_mfma_f32_16x16x32_bf16 v[44:47], v[132:135], v[214:217], v[44:47]
	v_mfma_f32_16x16x32_bf16 v[40:43], v[140:143], v[214:217], v[40:43]
	v_mfma_f32_16x16x32_bf16 v[28:31], v[132:135], v[222:225], v[28:31]
	v_mfma_f32_16x16x32_bf16 v[24:27], v[140:143], v[222:225], v[24:27]
	v_mfma_f32_16x16x32_bf16 v[12:15], v[132:135], v[230:233], v[12:15]
	v_mfma_f32_16x16x32_bf16 v[8:11], v[140:143], v[230:233], v[8:11]
	s_setprio 0
	s_setprio 1
	v_mfma_f32_16x16x32_bf16 v[52:55], v[160:163], v[202:205], v[52:55]
	v_mfma_f32_16x16x32_bf16 v[48:51], v[194:197], v[202:205], v[48:51]
	v_mfma_f32_16x16x32_bf16 v[36:39], v[160:163], v[210:213], v[36:39]
	v_mfma_f32_16x16x32_bf16 v[32:35], v[194:197], v[210:213], v[32:35]
	v_mfma_f32_16x16x32_bf16 v[20:23], v[160:163], v[218:221], v[20:23]
	v_mfma_f32_16x16x32_bf16 v[16:19], v[194:197], v[218:221], v[16:19]
	v_mfma_f32_16x16x32_bf16 v[4:7], v[160:163], v[226:229], v[4:7]
	v_mfma_f32_16x16x32_bf16 v[0:3], v[194:197], v[226:229], v[0:3]
	v_mfma_f32_16x16x32_bf16 v[52:55], v[174:177], v[206:209], v[52:55]
	v_mfma_f32_16x16x32_bf16 v[48:51], v[198:201], v[206:209], v[48:51]
	v_mfma_f32_16x16x32_bf16 v[36:39], v[174:177], v[214:217], v[36:39]
	v_mfma_f32_16x16x32_bf16 v[32:35], v[198:201], v[214:217], v[32:35]
	v_mfma_f32_16x16x32_bf16 v[20:23], v[174:177], v[222:225], v[20:23]
	v_mfma_f32_16x16x32_bf16 v[16:19], v[198:201], v[222:225], v[16:19]
	v_mfma_f32_16x16x32_bf16 v[4:7], v[174:177], v[230:233], v[4:7]
	v_mfma_f32_16x16x32_bf16 v[0:3], v[198:201], v[230:233], v[0:3]
	s_setprio 0
	s_barrier
	s_add_i32 s57, 0, 0x18000
	s_add_i32 s68, 0, 0x1c000
	v_add_u32_e32 v140, s57, v169
	v_add_u32_e32 v148, s68, v169
	ds_read_b128 v[128:131], v140
	ds_read_b128 v[132:135], v140 offset:1024
	ds_read_b128 v[136:139], v140 offset:2048
	ds_read_b128 v[140:143], v140 offset:3072
	ds_read_b128 v[160:163], v148
	ds_read_b128 v[174:177], v148 offset:1024
	ds_read_b128 v[194:197], v148 offset:2048
	ds_read_b128 v[198:201], v148 offset:3072
	s_add_u32 s66, s66, 0x40000
	s_addc_u32 s67, s67, 0
	s_mov_b32 m0, s88
	v_lshl_add_u64 v[188:189], s[66:67], 0, v[144:145]
	ds_read_b128 v[202:205], v183 offset:32768
	ds_read_b128 v[206:209], v183 offset:33792
	ds_read_b128 v[210:213], v183 offset:34816
	ds_read_b128 v[214:217], v183 offset:35840
	ds_read_b128 v[218:221], v183 offset:36864
	ds_read_b128 v[222:225], v183 offset:37888
	ds_read_b128 v[226:229], v183 offset:38912
	ds_read_b128 v[230:233], v183 offset:39936
	global_load_lds_dwordx4 v[188:189], off
	v_lshl_add_u64 v[188:189], s[66:67], 0, v[146:147]
	s_mov_b32 m0, s89
	s_nop 0
	global_load_lds_dwordx4 v[188:189], off
	s_waitcnt vmcnt(8)
	s_waitcnt lgkmcnt(0)
	s_barrier
	s_setprio 1
	v_mfma_f32_16x16x32_bf16 v[124:127], v[128:131], v[202:205], v[124:127]
	v_mfma_f32_16x16x32_bf16 v[120:123], v[136:139], v[202:205], v[120:123]
	v_mfma_f32_16x16x32_bf16 v[108:111], v[128:131], v[210:213], v[108:111]
	v_mfma_f32_16x16x32_bf16 v[104:107], v[136:139], v[210:213], v[104:107]
	v_mfma_f32_16x16x32_bf16 v[92:95], v[128:131], v[218:221], v[92:95]
	v_mfma_f32_16x16x32_bf16 v[88:91], v[136:139], v[218:221], v[88:91]
	v_mfma_f32_16x16x32_bf16 v[76:79], v[128:131], v[226:229], v[76:79]
	v_mfma_f32_16x16x32_bf16 v[72:75], v[136:139], v[226:229], v[72:75]
	v_mfma_f32_16x16x32_bf16 v[124:127], v[132:135], v[206:209], v[124:127]
	v_mfma_f32_16x16x32_bf16 v[120:123], v[140:143], v[206:209], v[120:123]
	v_mfma_f32_16x16x32_bf16 v[108:111], v[132:135], v[214:217], v[108:111]
	v_mfma_f32_16x16x32_bf16 v[104:107], v[140:143], v[214:217], v[104:107]
	v_mfma_f32_16x16x32_bf16 v[92:95], v[132:135], v[222:225], v[92:95]
	v_mfma_f32_16x16x32_bf16 v[88:91], v[140:143], v[222:225], v[88:91]
	v_mfma_f32_16x16x32_bf16 v[76:79], v[132:135], v[230:233], v[76:79]
	v_mfma_f32_16x16x32_bf16 v[72:75], v[140:143], v[230:233], v[72:75]
	s_setprio 0
	s_setprio 1
	v_mfma_f32_16x16x32_bf16 v[116:119], v[160:163], v[202:205], v[116:119]
	v_mfma_f32_16x16x32_bf16 v[112:115], v[194:197], v[202:205], v[112:115]
	v_mfma_f32_16x16x32_bf16 v[100:103], v[160:163], v[210:213], v[100:103]
	v_mfma_f32_16x16x32_bf16 v[96:99], v[194:197], v[210:213], v[96:99]
	v_mfma_f32_16x16x32_bf16 v[84:87], v[160:163], v[218:221], v[84:87]
	v_mfma_f32_16x16x32_bf16 v[80:83], v[194:197], v[218:221], v[80:83]
	v_mfma_f32_16x16x32_bf16 v[68:71], v[160:163], v[226:229], v[68:71]
	v_mfma_f32_16x16x32_bf16 v[64:67], v[194:197], v[226:229], v[64:67]
	v_mfma_f32_16x16x32_bf16 v[116:119], v[174:177], v[206:209], v[116:119]
	v_mfma_f32_16x16x32_bf16 v[112:115], v[198:201], v[206:209], v[112:115]
	v_mfma_f32_16x16x32_bf16 v[100:103], v[174:177], v[214:217], v[100:103]
	v_mfma_f32_16x16x32_bf16 v[96:99], v[198:201], v[214:217], v[96:99]
	v_mfma_f32_16x16x32_bf16 v[84:87], v[174:177], v[222:225], v[84:87]
	v_mfma_f32_16x16x32_bf16 v[80:83], v[198:201], v[222:225], v[80:83]
	v_mfma_f32_16x16x32_bf16 v[68:71], v[174:177], v[230:233], v[68:71]
	v_mfma_f32_16x16x32_bf16 v[64:67], v[198:201], v[230:233], v[64:67]
	s_setprio 0
	s_barrier
	s_add_i32 s57, s57, s85
	v_lshl_add_u64 v[166:167], v[166:167], 0, s[42:43]
	s_mov_b32 m0, s57
	ds_read_b128 v[202:205], v183 offset:49152
	ds_read_b128 v[206:209], v183 offset:50176
	ds_read_b128 v[210:213], v183 offset:51200
	ds_read_b128 v[214:217], v183 offset:52224
	ds_read_b128 v[218:221], v183 offset:53248
	ds_read_b128 v[222:225], v183 offset:54272
	ds_read_b128 v[226:229], v183 offset:55296
	ds_read_b128 v[230:233], v183 offset:56320
	global_load_lds_dwordx4 v[166:167], off
	s_add_i32 m0, s57, 0x2000
	s_add_u32 s64, s64, 0x40080
	v_lshl_add_u64 v[166:167], v[170:171], 0, s[42:43]
	s_addc_u32 s65, s65, 0
	s_add_i32 s57, s68, s85
	global_load_lds_dwordx4 v[166:167], off
	v_lshl_add_u64 v[166:167], s[64:65], 0, v[144:145]
	s_mov_b32 m0, s57
	s_nop 0
	global_load_lds_dwordx4 v[166:167], off
	v_lshl_add_u64 v[166:167], s[64:65], 0, v[146:147]
	s_add_i32 m0, s57, 0x2000
	s_nop 0
	global_load_lds_dwordx4 v[166:167], off
	v_lshl_add_u64 v[166:167], v[180:181], 0, s[42:43]
	s_mov_b32 m0, s94
	s_nop 0
	global_load_lds_dwordx4 v[166:167], off
	v_lshl_add_u64 v[166:167], v[184:185], 0, s[42:43]
	s_mov_b32 m0, s95
	s_nop 0
	global_load_lds_dwordx4 v[166:167], off
	s_waitcnt vmcnt(8)
	s_waitcnt lgkmcnt(0)
	s_barrier
	s_setprio 1
	v_mfma_f32_16x16x32_bf16 v[60:63], v[128:131], v[202:205], v[60:63]
	v_mfma_f32_16x16x32_bf16 v[56:59], v[136:139], v[202:205], v[56:59]
	v_mfma_f32_16x16x32_bf16 v[44:47], v[128:131], v[210:213], v[44:47]
	v_mfma_f32_16x16x32_bf16 v[40:43], v[136:139], v[210:213], v[40:43]
	v_mfma_f32_16x16x32_bf16 v[28:31], v[128:131], v[218:221], v[28:31]
	v_mfma_f32_16x16x32_bf16 v[24:27], v[136:139], v[218:221], v[24:27]
	v_mfma_f32_16x16x32_bf16 v[12:15], v[128:131], v[226:229], v[12:15]
	v_mfma_f32_16x16x32_bf16 v[8:11], v[136:139], v[226:229], v[8:11]
	v_mfma_f32_16x16x32_bf16 v[60:63], v[132:135], v[206:209], v[60:63]
	v_mfma_f32_16x16x32_bf16 v[56:59], v[140:143], v[206:209], v[56:59]
	v_mfma_f32_16x16x32_bf16 v[44:47], v[132:135], v[214:217], v[44:47]
	v_mfma_f32_16x16x32_bf16 v[40:43], v[140:143], v[214:217], v[40:43]
	v_mfma_f32_16x16x32_bf16 v[28:31], v[132:135], v[222:225], v[28:31]
	v_mfma_f32_16x16x32_bf16 v[24:27], v[140:143], v[222:225], v[24:27]
	v_mfma_f32_16x16x32_bf16 v[12:15], v[132:135], v[230:233], v[12:15]
	v_mfma_f32_16x16x32_bf16 v[8:11], v[140:143], v[230:233], v[8:11]
	s_setprio 0
	s_setprio 1
	v_mfma_f32_16x16x32_bf16 v[52:55], v[160:163], v[202:205], v[52:55]
	v_mfma_f32_16x16x32_bf16 v[48:51], v[194:197], v[202:205], v[48:51]
	v_mfma_f32_16x16x32_bf16 v[36:39], v[160:163], v[210:213], v[36:39]
	v_mfma_f32_16x16x32_bf16 v[32:35], v[194:197], v[210:213], v[32:35]
	v_mfma_f32_16x16x32_bf16 v[20:23], v[160:163], v[218:221], v[20:23]
	v_mfma_f32_16x16x32_bf16 v[16:19], v[194:197], v[218:221], v[16:19]
	v_mfma_f32_16x16x32_bf16 v[4:7], v[160:163], v[226:229], v[4:7]
	v_mfma_f32_16x16x32_bf16 v[0:3], v[194:197], v[226:229], v[0:3]
	v_mfma_f32_16x16x32_bf16 v[52:55], v[174:177], v[206:209], v[52:55]
	v_mfma_f32_16x16x32_bf16 v[48:51], v[198:201], v[206:209], v[48:51]
	v_mfma_f32_16x16x32_bf16 v[36:39], v[174:177], v[214:217], v[36:39]
	v_mfma_f32_16x16x32_bf16 v[32:35], v[198:201], v[214:217], v[32:35]
	v_mfma_f32_16x16x32_bf16 v[20:23], v[174:177], v[222:225], v[20:23]
	v_mfma_f32_16x16x32_bf16 v[16:19], v[198:201], v[222:225], v[16:19]
	v_mfma_f32_16x16x32_bf16 v[4:7], v[174:177], v[230:233], v[4:7]
	v_mfma_f32_16x16x32_bf16 v[0:3], v[198:201], v[230:233], v[0:3]
	s_setprio 0
	s_barrier
	s_add_i32 s55, s55, 2
	s_add_u32 s62, s62, 0x100
	s_addc_u32 s63, s63, 0
	s_add_u32 s22, s22, 0x100
	s_addc_u32 s23, s23, 0
	s_cmp_gt_u32 s55, 13
	s_cbranch_scc0 .LBB0_552
	s_and_b64 vcc, exec, s[44:45]
	s_cbranch_vccz .LBB0_555
	s_barrier

.Lkv_nopf:
	s_setprio 1
	v_mfma_f32_16x16x32_bf16 v[124:127], v[150:153], v[182:185], v[124:127]
	v_mfma_f32_16x16x32_bf16 v[120:123], v[158:161], v[182:185], v[120:123]
	v_mfma_f32_16x16x32_bf16 v[108:111], v[150:153], v[190:193], v[108:111]
	v_mfma_f32_16x16x32_bf16 v[104:107], v[158:161], v[190:193], v[104:107]
	v_mfma_f32_16x16x32_bf16 v[92:95], v[150:153], v[198:201], v[92:95]
	v_mfma_f32_16x16x32_bf16 v[88:91], v[158:161], v[198:201], v[88:91]
	v_mfma_f32_16x16x32_bf16 v[76:79], v[150:153], v[206:209], v[76:79]
	v_mfma_f32_16x16x32_bf16 v[72:75], v[158:161], v[206:209], v[72:75]
	v_mfma_f32_16x16x32_bf16 v[124:127], v[154:157], v[186:189], v[124:127]
	v_mfma_f32_16x16x32_bf16 v[120:123], v[162:165], v[186:189], v[120:123]
	v_mfma_f32_16x16x32_bf16 v[108:111], v[154:157], v[194:197], v[108:111]
	v_mfma_f32_16x16x32_bf16 v[104:107], v[162:165], v[194:197], v[104:107]
	v_mfma_f32_16x16x32_bf16 v[92:95], v[154:157], v[202:205], v[92:95]
	v_mfma_f32_16x16x32_bf16 v[88:91], v[162:165], v[202:205], v[88:91]
	v_mfma_f32_16x16x32_bf16 v[76:79], v[154:157], v[210:213], v[76:79]
	v_mfma_f32_16x16x32_bf16 v[72:75], v[162:165], v[210:213], v[72:75]
	s_setprio 0
	s_setprio 1
	v_mfma_f32_16x16x32_bf16 v[116:119], v[166:169], v[182:185], v[116:119]
	v_mfma_f32_16x16x32_bf16 v[112:115], v[174:177], v[182:185], v[112:115]
	v_mfma_f32_16x16x32_bf16 v[100:103], v[166:169], v[190:193], v[100:103]
	v_mfma_f32_16x16x32_bf16 v[96:99], v[174:177], v[190:193], v[96:99]
	v_mfma_f32_16x16x32_bf16 v[84:87], v[166:169], v[198:201], v[84:87]
	v_mfma_f32_16x16x32_bf16 v[80:83], v[174:177], v[198:201], v[80:83]
	v_mfma_f32_16x16x32_bf16 v[68:71], v[166:169], v[206:209], v[68:71]
	v_mfma_f32_16x16x32_bf16 v[64:67], v[174:177], v[206:209], v[64:67]
	v_mfma_f32_16x16x32_bf16 v[116:119], v[170:173], v[186:189], v[116:119]
	v_mfma_f32_16x16x32_bf16 v[112:115], v[178:181], v[186:189], v[112:115]
	v_mfma_f32_16x16x32_bf16 v[100:103], v[170:173], v[194:197], v[100:103]
	v_mfma_f32_16x16x32_bf16 v[96:99], v[178:181], v[194:197], v[96:99]
	v_mfma_f32_16x16x32_bf16 v[84:87], v[170:173], v[202:205], v[84:87]
	v_mfma_f32_16x16x32_bf16 v[80:83], v[178:181], v[202:205], v[80:83]
	v_mfma_f32_16x16x32_bf16 v[68:71], v[170:173], v[210:213], v[68:71]
	v_mfma_f32_16x16x32_bf16 v[64:67], v[178:181], v[210:213], v[64:67]
	s_setprio 0
	s_barrier
	s_mov_b32 m0, s93
	v_lshl_add_u64 v[138:139], s[52:53], 0, v[130:131]
	ds_read_b128 v[182:185], v146 offset:16384
	ds_read_b128 v[186:189], v146 offset:17408
	ds_read_b128 v[190:193], v146 offset:18432
	ds_read_b128 v[194:197], v146 offset:19456
	ds_read_b128 v[198:201], v146 offset:20480
	ds_read_b128 v[202:205], v146 offset:21504
	ds_read_b128 v[206:209], v146 offset:22528
	ds_read_b128 v[210:213], v146 offset:23552
	global_load_lds_dwordx4 v[138:139], off
	v_lshl_add_u64 v[214:215], s[52:53], 0, v[128:129]
	s_mov_b32 m0, s90
	v_lshl_add_u64 v[216:217], s[54:55], 0, v[130:131]
	global_load_lds_dwordx4 v[214:215], off
	s_mov_b32 m0, s92
	v_lshl_add_u64 v[218:219], s[50:51], 0, v[128:129]
	global_load_lds_dwordx4 v[216:217], off
	v_lshl_add_u64 v[216:217], s[54:55], 0, v[128:129]
	s_mov_b32 m0, s91
	s_nop 0
	global_load_lds_dwordx4 v[216:217], off
	v_lshl_add_u64 v[216:217], s[50:51], 0, v[130:131]
	s_mov_b32 m0, s61
	s_nop 0
	global_load_lds_dwordx4 v[216:217], off
	s_mov_b32 m0, s62
	s_nop 0
	global_load_lds_dwordx4 v[218:219], off
	s_waitcnt vmcnt(8)
	s_waitcnt lgkmcnt(0)
	s_barrier
	s_setprio 1
	v_mfma_f32_16x16x32_bf16 v[60:63], v[150:153], v[182:185], v[60:63]
	v_mfma_f32_16x16x32_bf16 v[56:59], v[158:161], v[182:185], v[56:59]
	v_mfma_f32_16x16x32_bf16 v[44:47], v[150:153], v[190:193], v[44:47]
	v_mfma_f32_16x16x32_bf16 v[40:43], v[158:161], v[190:193], v[40:43]
	v_mfma_f32_16x16x32_bf16 v[28:31], v[150:153], v[198:201], v[28:31]
	v_mfma_f32_16x16x32_bf16 v[24:27], v[158:161], v[198:201], v[24:27]
	v_mfma_f32_16x16x32_bf16 v[12:15], v[150:153], v[206:209], v[12:15]
	v_mfma_f32_16x16x32_bf16 v[8:11], v[158:161], v[206:209], v[8:11]
	v_mfma_f32_16x16x32_bf16 v[60:63], v[154:157], v[186:189], v[60:63]
	v_mfma_f32_16x16x32_bf16 v[56:59], v[162:165], v[186:189], v[56:59]
	v_mfma_f32_16x16x32_bf16 v[44:47], v[154:157], v[194:197], v[44:47]
	v_mfma_f32_16x16x32_bf16 v[40:43], v[162:165], v[194:197], v[40:43]
	v_mfma_f32_16x16x32_bf16 v[28:31], v[154:157], v[202:205], v[28:31]
	v_mfma_f32_16x16x32_bf16 v[24:27], v[162:165], v[202:205], v[24:27]
	v_mfma_f32_16x16x32_bf16 v[12:15], v[154:157], v[210:213], v[12:15]
	v_mfma_f32_16x16x32_bf16 v[8:11], v[162:165], v[210:213], v[8:11]
	s_setprio 0
	s_setprio 1
	v_mfma_f32_16x16x32_bf16 v[52:55], v[166:169], v[182:185], v[52:55]
	v_mfma_f32_16x16x32_bf16 v[48:51], v[174:177], v[182:185], v[48:51]
	v_mfma_f32_16x16x32_bf16 v[36:39], v[166:169], v[190:193], v[36:39]
	v_mfma_f32_16x16x32_bf16 v[32:35], v[174:177], v[190:193], v[32:35]
	v_mfma_f32_16x16x32_bf16 v[20:23], v[166:169], v[198:201], v[20:23]
	v_mfma_f32_16x16x32_bf16 v[16:19], v[174:177], v[198:201], v[16:19]
	v_mfma_f32_16x16x32_bf16 v[4:7], v[166:169], v[206:209], v[4:7]
	v_mfma_f32_16x16x32_bf16 v[0:3], v[174:177], v[206:209], v[0:3]
	v_mfma_f32_16x16x32_bf16 v[52:55], v[170:173], v[186:189], v[52:55]
	v_mfma_f32_16x16x32_bf16 v[48:51], v[178:181], v[186:189], v[48:51]
	v_mfma_f32_16x16x32_bf16 v[36:39], v[170:173], v[194:197], v[36:39]
	v_mfma_f32_16x16x32_bf16 v[32:35], v[178:181], v[194:197], v[32:35]
	v_mfma_f32_16x16x32_bf16 v[20:23], v[170:173], v[202:205], v[20:23]
	v_mfma_f32_16x16x32_bf16 v[16:19], v[178:181], v[202:205], v[16:19]
	v_mfma_f32_16x16x32_bf16 v[4:7], v[170:173], v[210:213], v[4:7]
	v_mfma_f32_16x16x32_bf16 v[0:3], v[178:181], v[210:213], v[0:3]
	s_setprio 0
	s_barrier
	v_add_u32_e32 v132, s89, v143
	ds_read_b128 v[150:153], v132
	ds_read_b128 v[154:157], v132 offset:1024
	ds_read_b128 v[158:161], v132 offset:2048
	ds_read_b128 v[162:165], v132 offset:3072
	v_add_u32_e32 v132, s88, v143
	ds_read_b128 v[166:169], v132
	ds_read_b128 v[170:173], v132 offset:1024
	ds_read_b128 v[174:177], v132 offset:2048
	ds_read_b128 v[178:181], v132 offset:3072
	s_mov_b32 m0, s63
	v_lshl_add_u64 v[220:221], s[48:49], 0, v[130:131]
	ds_read_b128 v[182:185], v146 offset:32768
	ds_read_b128 v[186:189], v146 offset:33792
	ds_read_b128 v[190:193], v146 offset:34816
	ds_read_b128 v[194:197], v146 offset:35840
	ds_read_b128 v[198:201], v146 offset:36864
	ds_read_b128 v[202:205], v146 offset:37888
	ds_read_b128 v[206:209], v146 offset:38912
	ds_read_b128 v[210:213], v146 offset:39936
	global_load_lds_dwordx4 v[220:221], off
	v_lshl_add_u64 v[220:221], s[48:49], 0, v[128:129]
	s_mov_b32 m0, s64
	s_nop 0
	global_load_lds_dwordx4 v[220:221], off
	s_waitcnt vmcnt(8)
	s_waitcnt lgkmcnt(0)
	s_barrier
	s_setprio 1
	v_mfma_f32_16x16x32_bf16 v[124:127], v[150:153], v[182:185], v[124:127]
	v_mfma_f32_16x16x32_bf16 v[120:123], v[158:161], v[182:185], v[120:123]
	v_mfma_f32_16x16x32_bf16 v[108:111], v[150:153], v[190:193], v[108:111]
	v_mfma_f32_16x16x32_bf16 v[104:107], v[158:161], v[190:193], v[104:107]
	v_mfma_f32_16x16x32_bf16 v[92:95], v[150:153], v[198:201], v[92:95]
	v_mfma_f32_16x16x32_bf16 v[88:91], v[158:161], v[198:201], v[88:91]
	v_mfma_f32_16x16x32_bf16 v[76:79], v[150:153], v[206:209], v[76:79]
	v_mfma_f32_16x16x32_bf16 v[72:75], v[158:161], v[206:209], v[72:75]
	v_mfma_f32_16x16x32_bf16 v[124:127], v[154:157], v[186:189], v[124:127]
	v_mfma_f32_16x16x32_bf16 v[120:123], v[162:165], v[186:189], v[120:123]
	v_mfma_f32_16x16x32_bf16 v[108:111], v[154:157], v[194:197], v[108:111]
	v_mfma_f32_16x16x32_bf16 v[104:107], v[162:165], v[194:197], v[104:107]
	v_mfma_f32_16x16x32_bf16 v[92:95], v[154:157], v[202:205], v[92:95]
	v_mfma_f32_16x16x32_bf16 v[88:91], v[162:165], v[202:205], v[88:91]
	v_mfma_f32_16x16x32_bf16 v[76:79], v[154:157], v[210:213], v[76:79]
	v_mfma_f32_16x16x32_bf16 v[72:75], v[162:165], v[210:213], v[72:75]
	s_setprio 0
	s_setprio 1
	v_mfma_f32_16x16x32_bf16 v[116:119], v[166:169], v[182:185], v[116:119]
	v_mfma_f32_16x16x32_bf16 v[112:115], v[174:177], v[182:185], v[112:115]
	v_mfma_f32_16x16x32_bf16 v[100:103], v[166:169], v[190:193], v[100:103]
	v_mfma_f32_16x16x32_bf16 v[96:99], v[174:177], v[190:193], v[96:99]
	v_mfma_f32_16x16x32_bf16 v[84:87], v[166:169], v[198:201], v[84:87]
	v_mfma_f32_16x16x32_bf16 v[80:83], v[174:177], v[198:201], v[80:83]
	v_mfma_f32_16x16x32_bf16 v[68:71], v[166:169], v[206:209], v[68:71]
	v_mfma_f32_16x16x32_bf16 v[64:67], v[174:177], v[206:209], v[64:67]
	v_mfma_f32_16x16x32_bf16 v[116:119], v[170:173], v[186:189], v[116:119]
	v_mfma_f32_16x16x32_bf16 v[112:115], v[178:181], v[186:189], v[112:115]
	v_mfma_f32_16x16x32_bf16 v[100:103], v[170:173], v[194:197], v[100:103]
	v_mfma_f32_16x16x32_bf16 v[96:99], v[178:181], v[194:197], v[96:99]
	v_mfma_f32_16x16x32_bf16 v[84:87], v[170:173], v[202:205], v[84:87]
	v_mfma_f32_16x16x32_bf16 v[80:83], v[178:181], v[202:205], v[80:83]
	v_mfma_f32_16x16x32_bf16 v[68:71], v[170:173], v[210:213], v[68:71]
	v_mfma_f32_16x16x32_bf16 v[64:67], v[178:181], v[210:213], v[64:67]
	s_setprio 0
	s_barrier
	s_mov_b32 m0, s87
	v_lshl_add_u64 v[138:139], v[138:139], 0, s[16:17]
	ds_read_b128 v[182:185], v146 offset:49152
	ds_read_b128 v[186:189], v146 offset:50176
	ds_read_b128 v[190:193], v146 offset:51200
	ds_read_b128 v[194:197], v146 offset:52224
	ds_read_b128 v[198:201], v146 offset:53248
	ds_read_b128 v[202:205], v146 offset:54272
	ds_read_b128 v[206:209], v146 offset:55296
	ds_read_b128 v[210:213], v146 offset:56320
	global_load_lds_dwordx4 v[138:139], off
	v_lshl_add_u64 v[138:139], v[214:215], 0, s[16:17]
	s_mov_b32 m0, s85
	s_nop 0
	global_load_lds_dwordx4 v[138:139], off
	v_lshl_add_u64 v[138:139], s[46:47], 0, v[130:131]
	s_mov_b32 m0, s86
	s_nop 0
	global_load_lds_dwordx4 v[138:139], off
	v_lshl_add_u64 v[138:139], s[46:47], 0, v[128:129]
	s_mov_b32 m0, s84
	s_nop 0
	global_load_lds_dwordx4 v[138:139], off
	v_lshl_add_u64 v[138:139], v[216:217], 0, s[16:17]
	s_mov_b32 m0, s70
	s_nop 0
	global_load_lds_dwordx4 v[138:139], off
	v_lshl_add_u64 v[138:139], v[218:219], 0, s[16:17]
	s_mov_b32 m0, s71
	s_nop 0
	global_load_lds_dwordx4 v[138:139], off
	s_waitcnt vmcnt(8)
	s_waitcnt lgkmcnt(0)
	s_barrier
	s_setprio 1
	v_mfma_f32_16x16x32_bf16 v[60:63], v[150:153], v[182:185], v[60:63]
	v_mfma_f32_16x16x32_bf16 v[56:59], v[158:161], v[182:185], v[56:59]
	v_mfma_f32_16x16x32_bf16 v[44:47], v[150:153], v[190:193], v[44:47]
	v_mfma_f32_16x16x32_bf16 v[40:43], v[158:161], v[190:193], v[40:43]
	v_mfma_f32_16x16x32_bf16 v[28:31], v[150:153], v[198:201], v[28:31]
	v_mfma_f32_16x16x32_bf16 v[24:27], v[158:161], v[198:201], v[24:27]
	v_mfma_f32_16x16x32_bf16 v[12:15], v[150:153], v[206:209], v[12:15]
	v_mfma_f32_16x16x32_bf16 v[8:11], v[158:161], v[206:209], v[8:11]
	v_mfma_f32_16x16x32_bf16 v[60:63], v[154:157], v[186:189], v[60:63]
	v_mfma_f32_16x16x32_bf16 v[56:59], v[162:165], v[186:189], v[56:59]
	v_mfma_f32_16x16x32_bf16 v[44:47], v[154:157], v[194:197], v[44:47]
	v_mfma_f32_16x16x32_bf16 v[40:43], v[162:165], v[194:197], v[40:43]
	v_mfma_f32_16x16x32_bf16 v[28:31], v[154:157], v[202:205], v[28:31]
	v_mfma_f32_16x16x32_bf16 v[24:27], v[162:165], v[202:205], v[24:27]
	v_mfma_f32_16x16x32_bf16 v[12:15], v[154:157], v[210:213], v[12:15]
	v_mfma_f32_16x16x32_bf16 v[8:11], v[162:165], v[210:213], v[8:11]
	s_setprio 0
	s_setprio 1
	v_mfma_f32_16x16x32_bf16 v[52:55], v[166:169], v[182:185], v[52:55]
	v_mfma_f32_16x16x32_bf16 v[48:51], v[174:177], v[182:185], v[48:51]
	v_mfma_f32_16x16x32_bf16 v[36:39], v[166:169], v[190:193], v[36:39]
	v_mfma_f32_16x16x32_bf16 v[32:35], v[174:177], v[190:193], v[32:35]
	v_mfma_f32_16x16x32_bf16 v[20:23], v[166:169], v[198:201], v[20:23]
	v_mfma_f32_16x16x32_bf16 v[16:19], v[174:177], v[198:201], v[16:19]
	v_mfma_f32_16x16x32_bf16 v[4:7], v[166:169], v[206:209], v[4:7]
	v_mfma_f32_16x16x32_bf16 v[0:3], v[174:177], v[206:209], v[0:3]
	v_mfma_f32_16x16x32_bf16 v[52:55], v[170:173], v[186:189], v[52:55]
	v_mfma_f32_16x16x32_bf16 v[48:51], v[178:181], v[186:189], v[48:51]
	v_mfma_f32_16x16x32_bf16 v[36:39], v[170:173], v[194:197], v[36:39]
	v_mfma_f32_16x16x32_bf16 v[32:35], v[178:181], v[194:197], v[32:35]
	v_mfma_f32_16x16x32_bf16 v[20:23], v[170:173], v[202:205], v[20:23]
	v_mfma_f32_16x16x32_bf16 v[16:19], v[178:181], v[202:205], v[16:19]
	v_mfma_f32_16x16x32_bf16 v[4:7], v[170:173], v[210:213], v[4:7]
	v_mfma_f32_16x16x32_bf16 v[0:3], v[178:181], v[210:213], v[0:3]
	s_setprio 0
	s_barrier
	s_andn2_b64 vcc, exec, s[44:45]
	s_mov_b64 s[46:47], -1
	s_mov_b64 s[44:45], 0
	s_mov_b64 s[48:49], 0x100
	s_cbranch_vccz .LBB0_744
	s_and_b64 vcc, exec, s[20:21]
	s_cbranch_vccz .LBB0_747
	s_barrier

.LBB0_771:
	ds_read_b128 v[84:87], v208
	ds_read_b128 v[100:103], v208 offset:1024
	ds_read_b128 v[120:123], v208 offset:2048
	ds_read_b128 v[140:143], v208 offset:3072
	ds_read_b128 v[144:147], v209
	ds_read_b128 v[148:151], v209 offset:1024
	ds_read_b128 v[152:155], v209 offset:2048
	ds_read_b128 v[170:173], v209 offset:3072
	s_add_u32 s6, s8, 0x100
	s_addc_u32 s7, s9, 0
	s_cmp_eq_u32 s83, 2
	s_cselect_b32 s41, s35, s7
	s_cselect_b32 s40, s34, s6
	s_cselect_b32 s39, s37, s82
	s_cselect_b32 s38, s36, s81
	v_lshl_add_u64 v[214:215], s[8:9], 0, v[162:163]
	s_add_i32 m0, s42, 0xc000
	ds_read_b128 v[174:177], v210
	ds_read_b128 v[178:181], v210 offset:1024
	ds_read_b128 v[182:185], v210 offset:2048
	ds_read_b128 v[186:189], v210 offset:3072
	ds_read_b128 v[190:193], v210 offset:4096
	ds_read_b128 v[194:197], v210 offset:5120
	ds_read_b128 v[198:201], v210 offset:6144
	ds_read_b128 v[202:205], v210 offset:7168
	global_load_lds_dwordx4 v[214:215], off
	v_lshl_add_u64 v[214:215], s[8:9], 0, v[164:165]
	s_add_i32 m0, s42, 0xe000
	s_nop 0
	global_load_lds_dwordx4 v[214:215], off
	s_waitcnt vmcnt(8)
	s_waitcnt lgkmcnt(0)
	s_barrier
	s_setprio 1
	v_mfma_f32_16x16x32_bf16 v[136:139], v[84:87], v[174:177], v[136:139]
	v_mfma_f32_16x16x32_bf16 v[132:135], v[120:123], v[174:177], v[132:135]
	v_mfma_f32_16x16x32_bf16 v[116:119], v[84:87], v[182:185], v[116:119]
	v_mfma_f32_16x16x32_bf16 v[112:115], v[120:123], v[182:185], v[112:115]
	v_mfma_f32_16x16x32_bf16 v[96:99], v[84:87], v[190:193], v[96:99]
	v_mfma_f32_16x16x32_bf16 v[92:95], v[120:123], v[190:193], v[92:95]
	v_mfma_f32_16x16x32_bf16 v[76:79], v[84:87], v[198:201], v[76:79]
	v_mfma_f32_16x16x32_bf16 v[72:75], v[120:123], v[198:201], v[72:75]
	v_mfma_f32_16x16x32_bf16 v[136:139], v[100:103], v[178:181], v[136:139]
	v_mfma_f32_16x16x32_bf16 v[132:135], v[140:143], v[178:181], v[132:135]
	v_mfma_f32_16x16x32_bf16 v[116:119], v[100:103], v[186:189], v[116:119]
	v_mfma_f32_16x16x32_bf16 v[112:115], v[140:143], v[186:189], v[112:115]
	v_mfma_f32_16x16x32_bf16 v[96:99], v[100:103], v[194:197], v[96:99]
	v_mfma_f32_16x16x32_bf16 v[92:95], v[140:143], v[194:197], v[92:95]
	v_mfma_f32_16x16x32_bf16 v[76:79], v[100:103], v[202:205], v[76:79]
	v_mfma_f32_16x16x32_bf16 v[72:75], v[140:143], v[202:205], v[72:75]
	s_setprio 0
	s_setprio 1
	v_mfma_f32_16x16x32_bf16 v[128:131], v[144:147], v[174:177], v[128:131]
	v_mfma_f32_16x16x32_bf16 v[124:127], v[152:155], v[174:177], v[124:127]
	v_mfma_f32_16x16x32_bf16 v[108:111], v[144:147], v[182:185], v[108:111]
	v_mfma_f32_16x16x32_bf16 v[104:107], v[152:155], v[182:185], v[104:107]
	v_mfma_f32_16x16x32_bf16 v[88:91], v[144:147], v[190:193], v[88:91]
	v_mfma_f32_16x16x32_bf16 v[80:83], v[152:155], v[190:193], v[80:83]
	v_mfma_f32_16x16x32_bf16 v[68:71], v[144:147], v[198:201], v[68:71]
	v_mfma_f32_16x16x32_bf16 v[64:67], v[152:155], v[198:201], v[64:67]
	v_mfma_f32_16x16x32_bf16 v[128:131], v[148:151], v[178:181], v[128:131]
	v_mfma_f32_16x16x32_bf16 v[124:127], v[170:173], v[178:181], v[124:127]
	v_mfma_f32_16x16x32_bf16 v[108:111], v[148:151], v[186:189], v[108:111]
	v_mfma_f32_16x16x32_bf16 v[104:107], v[170:173], v[186:189], v[104:107]
	v_mfma_f32_16x16x32_bf16 v[88:91], v[148:151], v[194:197], v[88:91]
	v_mfma_f32_16x16x32_bf16 v[80:83], v[170:173], v[194:197], v[80:83]
	v_mfma_f32_16x16x32_bf16 v[68:71], v[148:151], v[202:205], v[68:71]
	v_mfma_f32_16x16x32_bf16 v[64:67], v[170:173], v[202:205], v[64:67]
	s_setprio 0
	s_barrier
	s_add_i32 s8, s61, s3
	v_lshl_add_u64 v[214:215], s[38:39], 0, v[156:157]
	s_mov_b32 m0, s8
	ds_read_b128 v[174:177], v210 offset:16384
	ds_read_b128 v[178:181], v210 offset:17408
	ds_read_b128 v[182:185], v210 offset:18432
	ds_read_b128 v[186:189], v210 offset:19456
	ds_read_b128 v[190:193], v210 offset:20480
	ds_read_b128 v[194:197], v210 offset:21504
	ds_read_b128 v[198:201], v210 offset:22528
	ds_read_b128 v[202:205], v210 offset:23552
	global_load_lds_dwordx4 v[214:215], off
	s_add_i32 m0, s8, 0x2000
	s_add_u32 s8, s38, 0x18000
	v_lshl_add_u64 v[216:217], s[38:39], 0, v[158:159]
	s_addc_u32 s9, s39, 0
	s_add_i32 s84, s62, s3
	global_load_lds_dwordx4 v[216:217], off
	v_lshl_add_u64 v[218:219], s[8:9], 0, v[156:157]
	s_mov_b32 m0, s84
	v_lshl_add_u64 v[220:221], s[40:41], 0, v[158:159]
	global_load_lds_dwordx4 v[218:219], off
	v_lshl_add_u64 v[218:219], s[8:9], 0, v[158:159]
	s_add_i32 m0, s84, 0x2000
	s_nop 0
	global_load_lds_dwordx4 v[218:219], off
	v_lshl_add_u64 v[218:219], s[40:41], 0, v[156:157]
	s_mov_b32 m0, s42
	s_nop 0
	global_load_lds_dwordx4 v[218:219], off
	s_mov_b32 m0, s43
	s_nop 0
	global_load_lds_dwordx4 v[220:221], off
	s_waitcnt vmcnt(8)
	s_waitcnt lgkmcnt(0)
	s_barrier
	s_setprio 1
	v_mfma_f32_16x16x32_bf16 v[60:63], v[84:87], v[174:177], v[60:63]
	v_mfma_f32_16x16x32_bf16 v[56:59], v[120:123], v[174:177], v[56:59]
	v_mfma_f32_16x16x32_bf16 v[44:47], v[84:87], v[182:185], v[44:47]
	v_mfma_f32_16x16x32_bf16 v[40:43], v[120:123], v[182:185], v[40:43]
	v_mfma_f32_16x16x32_bf16 v[28:31], v[84:87], v[190:193], v[28:31]
	v_mfma_f32_16x16x32_bf16 v[24:27], v[120:123], v[190:193], v[24:27]
	v_mfma_f32_16x16x32_bf16 v[12:15], v[84:87], v[198:201], v[12:15]
	v_mfma_f32_16x16x32_bf16 v[8:11], v[120:123], v[198:201], v[8:11]
	v_mfma_f32_16x16x32_bf16 v[60:63], v[100:103], v[178:181], v[60:63]
	v_mfma_f32_16x16x32_bf16 v[56:59], v[140:143], v[178:181], v[56:59]
	v_mfma_f32_16x16x32_bf16 v[44:47], v[100:103], v[186:189], v[44:47]
	v_mfma_f32_16x16x32_bf16 v[40:43], v[140:143], v[186:189], v[40:43]
	v_mfma_f32_16x16x32_bf16 v[28:31], v[100:103], v[194:197], v[28:31]
	v_mfma_f32_16x16x32_bf16 v[24:27], v[140:143], v[194:197], v[24:27]
	v_mfma_f32_16x16x32_bf16 v[12:15], v[100:103], v[202:205], v[12:15]
	v_mfma_f32_16x16x32_bf16 v[8:11], v[140:143], v[202:205], v[8:11]
	s_setprio 0
	s_setprio 1
	v_mfma_f32_16x16x32_bf16 v[52:55], v[144:147], v[174:177], v[52:55]
	v_mfma_f32_16x16x32_bf16 v[48:51], v[152:155], v[174:177], v[48:51]
	v_mfma_f32_16x16x32_bf16 v[36:39], v[144:147], v[182:185], v[36:39]
	v_mfma_f32_16x16x32_bf16 v[32:35], v[152:155], v[182:185], v[32:35]
	v_mfma_f32_16x16x32_bf16 v[20:23], v[144:147], v[190:193], v[20:23]
	v_mfma_f32_16x16x32_bf16 v[16:19], v[152:155], v[190:193], v[16:19]
	v_mfma_f32_16x16x32_bf16 v[4:7], v[144:147], v[198:201], v[4:7]
	v_mfma_f32_16x16x32_bf16 v[0:3], v[152:155], v[198:201], v[0:3]
	v_mfma_f32_16x16x32_bf16 v[52:55], v[148:151], v[178:181], v[52:55]
	v_mfma_f32_16x16x32_bf16 v[48:51], v[170:173], v[178:181], v[48:51]
	v_mfma_f32_16x16x32_bf16 v[36:39], v[148:151], v[186:189], v[36:39]
	v_mfma_f32_16x16x32_bf16 v[32:35], v[170:173], v[186:189], v[32:35]
	v_mfma_f32_16x16x32_bf16 v[20:23], v[148:151], v[194:197], v[20:23]
	v_mfma_f32_16x16x32_bf16 v[16:19], v[170:173], v[194:197], v[16:19]
	v_mfma_f32_16x16x32_bf16 v[4:7], v[148:151], v[202:205], v[4:7]
	v_mfma_f32_16x16x32_bf16 v[0:3], v[170:173], v[202:205], v[0:3]
	s_setprio 0
	s_barrier
	s_add_i32 s84, 0, 0x18000
	s_add_i32 s85, 0, 0x1c000
	v_add_u32_e32 v140, s84, v207
	v_add_u32_e32 v160, s85, v207
	ds_read_b128 v[84:87], v140
	ds_read_b128 v[100:103], v140 offset:1024
	ds_read_b128 v[120:123], v140 offset:2048
	ds_read_b128 v[140:143], v140 offset:3072
	ds_read_b128 v[144:147], v160
	ds_read_b128 v[148:151], v160 offset:1024
	ds_read_b128 v[152:155], v160 offset:2048
	ds_read_b128 v[170:173], v160 offset:3072
	s_add_u32 s8, s40, 0x18000
	s_addc_u32 s9, s41, 0
	s_mov_b32 m0, s44
	v_lshl_add_u64 v[222:223], s[8:9], 0, v[156:157]
	ds_read_b128 v[174:177], v210 offset:32768
	ds_read_b128 v[178:181], v210 offset:33792
	ds_read_b128 v[182:185], v210 offset:34816
	ds_read_b128 v[186:189], v210 offset:35840
	ds_read_b128 v[190:193], v210 offset:36864
	ds_read_b128 v[194:197], v210 offset:37888
	ds_read_b128 v[198:201], v210 offset:38912
	ds_read_b128 v[202:205], v210 offset:39936
	global_load_lds_dwordx4 v[222:223], off
	v_lshl_add_u64 v[222:223], s[8:9], 0, v[158:159]
	s_mov_b32 m0, s45
	s_nop 0
	global_load_lds_dwordx4 v[222:223], off
	s_waitcnt vmcnt(8)
	s_waitcnt lgkmcnt(0)
	s_barrier
	s_setprio 1
	v_mfma_f32_16x16x32_bf16 v[136:139], v[84:87], v[174:177], v[136:139]
	v_mfma_f32_16x16x32_bf16 v[132:135], v[120:123], v[174:177], v[132:135]
	v_mfma_f32_16x16x32_bf16 v[116:119], v[84:87], v[182:185], v[116:119]
	v_mfma_f32_16x16x32_bf16 v[112:115], v[120:123], v[182:185], v[112:115]
	v_mfma_f32_16x16x32_bf16 v[96:99], v[84:87], v[190:193], v[96:99]
	v_mfma_f32_16x16x32_bf16 v[92:95], v[120:123], v[190:193], v[92:95]
	v_mfma_f32_16x16x32_bf16 v[76:79], v[84:87], v[198:201], v[76:79]
	v_mfma_f32_16x16x32_bf16 v[72:75], v[120:123], v[198:201], v[72:75]
	v_mfma_f32_16x16x32_bf16 v[136:139], v[100:103], v[178:181], v[136:139]
	v_mfma_f32_16x16x32_bf16 v[132:135], v[140:143], v[178:181], v[132:135]
	v_mfma_f32_16x16x32_bf16 v[116:119], v[100:103], v[186:189], v[116:119]
	v_mfma_f32_16x16x32_bf16 v[112:115], v[140:143], v[186:189], v[112:115]
	v_mfma_f32_16x16x32_bf16 v[96:99], v[100:103], v[194:197], v[96:99]
	v_mfma_f32_16x16x32_bf16 v[92:95], v[140:143], v[194:197], v[92:95]
	v_mfma_f32_16x16x32_bf16 v[76:79], v[100:103], v[202:205], v[76:79]
	v_mfma_f32_16x16x32_bf16 v[72:75], v[140:143], v[202:205], v[72:75]
	s_setprio 0
	s_setprio 1
	v_mfma_f32_16x16x32_bf16 v[128:131], v[144:147], v[174:177], v[128:131]
	v_mfma_f32_16x16x32_bf16 v[124:127], v[152:155], v[174:177], v[124:127]
	v_mfma_f32_16x16x32_bf16 v[108:111], v[144:147], v[182:185], v[108:111]
	v_mfma_f32_16x16x32_bf16 v[104:107], v[152:155], v[182:185], v[104:107]
	v_mfma_f32_16x16x32_bf16 v[88:91], v[144:147], v[190:193], v[88:91]
	v_mfma_f32_16x16x32_bf16 v[80:83], v[152:155], v[190:193], v[80:83]
	v_mfma_f32_16x16x32_bf16 v[68:71], v[144:147], v[198:201], v[68:71]
	v_mfma_f32_16x16x32_bf16 v[64:67], v[152:155], v[198:201], v[64:67]
	v_mfma_f32_16x16x32_bf16 v[128:131], v[148:151], v[178:181], v[128:131]
	v_mfma_f32_16x16x32_bf16 v[124:127], v[170:173], v[178:181], v[124:127]
	v_mfma_f32_16x16x32_bf16 v[108:111], v[148:151], v[186:189], v[108:111]
	v_mfma_f32_16x16x32_bf16 v[104:107], v[170:173], v[186:189], v[104:107]
	v_mfma_f32_16x16x32_bf16 v[88:91], v[148:151], v[194:197], v[88:91]
	v_mfma_f32_16x16x32_bf16 v[80:83], v[170:173], v[194:197], v[80:83]
	v_mfma_f32_16x16x32_bf16 v[68:71], v[148:151], v[202:205], v[68:71]
	v_mfma_f32_16x16x32_bf16 v[64:67], v[170:173], v[202:205], v[64:67]
	s_setprio 0
	s_barrier
	s_add_i32 s8, s84, s3
	v_lshl_add_u64 v[214:215], v[214:215], 0, s[20:21]
	s_mov_b32 m0, s8
	ds_read_b128 v[174:177], v210 offset:49152
	ds_read_b128 v[178:181], v210 offset:50176
	ds_read_b128 v[182:185], v210 offset:51200
	ds_read_b128 v[186:189], v210 offset:52224
	ds_read_b128 v[190:193], v210 offset:53248
	ds_read_b128 v[194:197], v210 offset:54272
	ds_read_b128 v[198:201], v210 offset:55296
	ds_read_b128 v[202:205], v210 offset:56320
	global_load_lds_dwordx4 v[214:215], off
	s_add_i32 m0, s8, 0x2000
	s_add_u32 s8, s38, 0x18080
	v_lshl_add_u64 v[214:215], v[216:217], 0, s[20:21]
	s_addc_u32 s9, s39, 0
	s_add_i32 s38, s85, s3
	global_load_lds_dwordx4 v[214:215], off
	v_lshl_add_u64 v[214:215], s[8:9], 0, v[156:157]
	s_mov_b32 m0, s38
	s_nop 0
	global_load_lds_dwordx4 v[214:215], off
	v_lshl_add_u64 v[214:215], s[8:9], 0, v[158:159]
	s_add_i32 m0, s38, 0x2000
	s_nop 0
	global_load_lds_dwordx4 v[214:215], off
	v_lshl_add_u64 v[214:215], v[218:219], 0, s[20:21]
	s_mov_b32 m0, s51
	s_nop 0
	global_load_lds_dwordx4 v[214:215], off
	v_lshl_add_u64 v[214:215], v[220:221], 0, s[20:21]
	s_mov_b32 m0, s52
	s_nop 0
	global_load_lds_dwordx4 v[214:215], off
	s_waitcnt vmcnt(8)
	s_waitcnt lgkmcnt(0)
	s_barrier
	s_setprio 1
	v_mfma_f32_16x16x32_bf16 v[60:63], v[84:87], v[174:177], v[60:63]
	v_mfma_f32_16x16x32_bf16 v[56:59], v[120:123], v[174:177], v[56:59]
	v_mfma_f32_16x16x32_bf16 v[44:47], v[84:87], v[182:185], v[44:47]
	v_mfma_f32_16x16x32_bf16 v[40:43], v[120:123], v[182:185], v[40:43]
	v_mfma_f32_16x16x32_bf16 v[28:31], v[84:87], v[190:193], v[28:31]
	v_mfma_f32_16x16x32_bf16 v[24:27], v[120:123], v[190:193], v[24:27]
	v_mfma_f32_16x16x32_bf16 v[12:15], v[84:87], v[198:201], v[12:15]
	v_mfma_f32_16x16x32_bf16 v[8:11], v[120:123], v[198:201], v[8:11]
	v_mfma_f32_16x16x32_bf16 v[60:63], v[100:103], v[178:181], v[60:63]
	v_mfma_f32_16x16x32_bf16 v[56:59], v[140:143], v[178:181], v[56:59]
	v_mfma_f32_16x16x32_bf16 v[44:47], v[100:103], v[186:189], v[44:47]
	v_mfma_f32_16x16x32_bf16 v[40:43], v[140:143], v[186:189], v[40:43]
	v_mfma_f32_16x16x32_bf16 v[28:31], v[100:103], v[194:197], v[28:31]
	v_mfma_f32_16x16x32_bf16 v[24:27], v[140:143], v[194:197], v[24:27]
	v_mfma_f32_16x16x32_bf16 v[12:15], v[100:103], v[202:205], v[12:15]
	v_mfma_f32_16x16x32_bf16 v[8:11], v[140:143], v[202:205], v[8:11]
	s_setprio 0
	s_setprio 1
	v_mfma_f32_16x16x32_bf16 v[52:55], v[144:147], v[174:177], v[52:55]
	v_mfma_f32_16x16x32_bf16 v[48:51], v[152:155], v[174:177], v[48:51]
	v_mfma_f32_16x16x32_bf16 v[36:39], v[144:147], v[182:185], v[36:39]
	v_mfma_f32_16x16x32_bf16 v[32:35], v[152:155], v[182:185], v[32:35]
	v_mfma_f32_16x16x32_bf16 v[20:23], v[144:147], v[190:193], v[20:23]
	v_mfma_f32_16x16x32_bf16 v[16:19], v[152:155], v[190:193], v[16:19]
	v_mfma_f32_16x16x32_bf16 v[4:7], v[144:147], v[198:201], v[4:7]
	v_mfma_f32_16x16x32_bf16 v[0:3], v[152:155], v[198:201], v[0:3]
	v_mfma_f32_16x16x32_bf16 v[52:55], v[148:151], v[178:181], v[52:55]
	v_mfma_f32_16x16x32_bf16 v[48:51], v[170:173], v[178:181], v[48:51]
	v_mfma_f32_16x16x32_bf16 v[36:39], v[148:151], v[186:189], v[36:39]
	v_mfma_f32_16x16x32_bf16 v[32:35], v[170:173], v[186:189], v[32:35]
	v_mfma_f32_16x16x32_bf16 v[20:23], v[148:151], v[194:197], v[20:23]
	v_mfma_f32_16x16x32_bf16 v[16:19], v[170:173], v[194:197], v[16:19]
	v_mfma_f32_16x16x32_bf16 v[4:7], v[148:151], v[202:205], v[4:7]
	v_mfma_f32_16x16x32_bf16 v[0:3], v[170:173], v[202:205], v[0:3]
	s_setprio 0
	s_barrier
	s_add_i32 s83, s83, 2
	s_add_u32 s81, s81, 0x100
	s_addc_u32 s82, s82, 0
	s_cmp_gt_u32 s83, 3
	s_mov_b64 s[8:9], s[6:7]
	s_cbranch_scc0 .LBB0_771
	s_and_b64 vcc, exec, s[30:31]
	s_cbranch_vccz .LBB0_774
	s_barrier

.LBB0_938:
	ds_read_b128 v[128:131], v175
	ds_read_b128 v[132:135], v175 offset:1024
	ds_read_b128 v[136:139], v175 offset:2048
	ds_read_b128 v[140:143], v175 offset:3072
	ds_read_b128 v[144:147], v176
	ds_read_b128 v[148:151], v176 offset:1024
	ds_read_b128 v[168:171], v176 offset:2048
	ds_read_b128 v[182:185], v176 offset:3072
	s_add_u32 s36, s6, 0xfffe0080
	s_addc_u32 s37, s7, -1
	s_cmp_eq_u32 s42, 4
	s_cselect_b32 s39, s9, s37
	s_cselect_b32 s38, s27, s36
	s_cselect_b32 s37, s23, s41
	s_cselect_b32 s36, s35, s40
	v_lshl_add_u64 v[218:219], s[6:7], 0, v[158:159]
	s_add_i32 m0, s48, 0xc000
	ds_read_b128 v[186:189], v177
	ds_read_b128 v[190:193], v177 offset:1024
	ds_read_b128 v[194:197], v177 offset:2048
	ds_read_b128 v[198:201], v177 offset:3072
	ds_read_b128 v[202:205], v177 offset:4096
	ds_read_b128 v[206:209], v177 offset:5120
	ds_read_b128 v[210:213], v177 offset:6144
	ds_read_b128 v[214:217], v177 offset:7168
	global_load_lds_dwordx4 v[218:219], off
	v_lshl_add_u64 v[218:219], s[6:7], 0, v[160:161]
	s_add_i32 m0, s48, 0xe000
	s_nop 0
	global_load_lds_dwordx4 v[218:219], off
	s_waitcnt vmcnt(8)
	s_waitcnt lgkmcnt(0)
	s_barrier
	s_setprio 1
	v_mfma_f32_16x16x32_bf16 v[124:127], v[128:131], v[186:189], v[124:127]
	v_mfma_f32_16x16x32_bf16 v[120:123], v[136:139], v[186:189], v[120:123]
	v_mfma_f32_16x16x32_bf16 v[112:115], v[128:131], v[194:197], v[112:115]
	v_mfma_f32_16x16x32_bf16 v[116:119], v[136:139], v[194:197], v[116:119]
	v_mfma_f32_16x16x32_bf16 v[96:99], v[128:131], v[202:205], v[96:99]
	v_mfma_f32_16x16x32_bf16 v[104:107], v[136:139], v[202:205], v[104:107]
	v_mfma_f32_16x16x32_bf16 v[76:79], v[128:131], v[210:213], v[76:79]
	v_mfma_f32_16x16x32_bf16 v[72:75], v[136:139], v[210:213], v[72:75]
	v_mfma_f32_16x16x32_bf16 v[124:127], v[132:135], v[190:193], v[124:127]
	v_mfma_f32_16x16x32_bf16 v[120:123], v[140:143], v[190:193], v[120:123]
	v_mfma_f32_16x16x32_bf16 v[112:115], v[132:135], v[198:201], v[112:115]
	v_mfma_f32_16x16x32_bf16 v[116:119], v[140:143], v[198:201], v[116:119]
	v_mfma_f32_16x16x32_bf16 v[96:99], v[132:135], v[206:209], v[96:99]
	v_mfma_f32_16x16x32_bf16 v[104:107], v[140:143], v[206:209], v[104:107]
	v_mfma_f32_16x16x32_bf16 v[76:79], v[132:135], v[214:217], v[76:79]
	v_mfma_f32_16x16x32_bf16 v[72:75], v[140:143], v[214:217], v[72:75]
	s_setprio 0
	s_setprio 1
	v_mfma_f32_16x16x32_bf16 v[108:111], v[144:147], v[186:189], v[108:111]
	v_mfma_f32_16x16x32_bf16 v[100:103], v[168:171], v[186:189], v[100:103]
	v_mfma_f32_16x16x32_bf16 v[88:91], v[144:147], v[194:197], v[88:91]
	v_mfma_f32_16x16x32_bf16 v[92:95], v[168:171], v[194:197], v[92:95]
	v_mfma_f32_16x16x32_bf16 v[84:87], v[144:147], v[202:205], v[84:87]
	v_mfma_f32_16x16x32_bf16 v[80:83], v[168:171], v[202:205], v[80:83]
	v_mfma_f32_16x16x32_bf16 v[68:71], v[144:147], v[210:213], v[68:71]
	v_mfma_f32_16x16x32_bf16 v[64:67], v[168:171], v[210:213], v[64:67]
	v_mfma_f32_16x16x32_bf16 v[108:111], v[148:151], v[190:193], v[108:111]
	v_mfma_f32_16x16x32_bf16 v[100:103], v[182:185], v[190:193], v[100:103]
	v_mfma_f32_16x16x32_bf16 v[88:91], v[148:151], v[198:201], v[88:91]
	v_mfma_f32_16x16x32_bf16 v[92:95], v[182:185], v[198:201], v[92:95]
	v_mfma_f32_16x16x32_bf16 v[84:87], v[148:151], v[206:209], v[84:87]
	v_mfma_f32_16x16x32_bf16 v[80:83], v[182:185], v[206:209], v[80:83]
	v_mfma_f32_16x16x32_bf16 v[68:71], v[148:151], v[214:217], v[68:71]
	v_mfma_f32_16x16x32_bf16 v[64:67], v[182:185], v[214:217], v[64:67]
	s_setprio 0
	s_barrier
	s_add_i32 s43, s72, s47
	v_lshl_add_u64 v[218:219], s[36:37], 0, v[152:153]
	s_mov_b32 m0, s43
	ds_read_b128 v[186:189], v177 offset:16384
	ds_read_b128 v[190:193], v177 offset:17408
	ds_read_b128 v[194:197], v177 offset:18432
	ds_read_b128 v[198:201], v177 offset:19456
	ds_read_b128 v[202:205], v177 offset:20480
	ds_read_b128 v[206:209], v177 offset:21504
	ds_read_b128 v[210:213], v177 offset:22528
	ds_read_b128 v[214:217], v177 offset:23552
	global_load_lds_dwordx4 v[218:219], off
	s_add_i32 m0, s43, 0x2000
	s_add_u32 s88, s36, 0x20000
	v_lshl_add_u64 v[220:221], s[36:37], 0, v[154:155]
	s_addc_u32 s89, s37, 0
	s_add_i32 s43, s73, s47
	global_load_lds_dwordx4 v[220:221], off
	v_lshl_add_u64 v[222:223], s[88:89], 0, v[152:153]
	s_mov_b32 m0, s43
	v_lshl_add_u64 v[224:225], s[38:39], 0, v[154:155]
	global_load_lds_dwordx4 v[222:223], off
	v_lshl_add_u64 v[222:223], s[88:89], 0, v[154:155]
	s_add_i32 m0, s43, 0x2000
	s_nop 0
	global_load_lds_dwordx4 v[222:223], off
	v_lshl_add_u64 v[222:223], s[38:39], 0, v[152:153]
	s_mov_b32 m0, s48
	s_nop 0
	global_load_lds_dwordx4 v[222:223], off
	s_mov_b32 m0, s49
	s_nop 0
	global_load_lds_dwordx4 v[224:225], off
	s_waitcnt vmcnt(8)
	s_waitcnt lgkmcnt(0)
	s_barrier
	s_setprio 1
	v_mfma_f32_16x16x32_bf16 v[60:63], v[128:131], v[186:189], v[60:63]
	v_mfma_f32_16x16x32_bf16 v[56:59], v[136:139], v[186:189], v[56:59]
	v_mfma_f32_16x16x32_bf16 v[44:47], v[128:131], v[194:197], v[44:47]
	v_mfma_f32_16x16x32_bf16 v[40:43], v[136:139], v[194:197], v[40:43]
	v_mfma_f32_16x16x32_bf16 v[28:31], v[128:131], v[202:205], v[28:31]
	v_mfma_f32_16x16x32_bf16 v[24:27], v[136:139], v[202:205], v[24:27]
	v_mfma_f32_16x16x32_bf16 v[12:15], v[128:131], v[210:213], v[12:15]
	v_mfma_f32_16x16x32_bf16 v[8:11], v[136:139], v[210:213], v[8:11]
	v_mfma_f32_16x16x32_bf16 v[60:63], v[132:135], v[190:193], v[60:63]
	v_mfma_f32_16x16x32_bf16 v[56:59], v[140:143], v[190:193], v[56:59]
	v_mfma_f32_16x16x32_bf16 v[44:47], v[132:135], v[198:201], v[44:47]
	v_mfma_f32_16x16x32_bf16 v[40:43], v[140:143], v[198:201], v[40:43]
	v_mfma_f32_16x16x32_bf16 v[28:31], v[132:135], v[206:209], v[28:31]
	v_mfma_f32_16x16x32_bf16 v[24:27], v[140:143], v[206:209], v[24:27]
	v_mfma_f32_16x16x32_bf16 v[12:15], v[132:135], v[214:217], v[12:15]
	v_mfma_f32_16x16x32_bf16 v[8:11], v[140:143], v[214:217], v[8:11]
	s_setprio 0
	s_setprio 1
	v_mfma_f32_16x16x32_bf16 v[52:55], v[144:147], v[186:189], v[52:55]
	v_mfma_f32_16x16x32_bf16 v[48:51], v[168:171], v[186:189], v[48:51]
	v_mfma_f32_16x16x32_bf16 v[36:39], v[144:147], v[194:197], v[36:39]
	v_mfma_f32_16x16x32_bf16 v[32:35], v[168:171], v[194:197], v[32:35]
	v_mfma_f32_16x16x32_bf16 v[20:23], v[144:147], v[202:205], v[20:23]
	v_mfma_f32_16x16x32_bf16 v[16:19], v[168:171], v[202:205], v[16:19]
	v_mfma_f32_16x16x32_bf16 v[4:7], v[144:147], v[210:213], v[4:7]
	v_mfma_f32_16x16x32_bf16 v[0:3], v[168:171], v[210:213], v[0:3]
	v_mfma_f32_16x16x32_bf16 v[52:55], v[148:151], v[190:193], v[52:55]
	v_mfma_f32_16x16x32_bf16 v[48:51], v[182:185], v[190:193], v[48:51]
	v_mfma_f32_16x16x32_bf16 v[36:39], v[148:151], v[198:201], v[36:39]
	v_mfma_f32_16x16x32_bf16 v[32:35], v[182:185], v[198:201], v[32:35]
	v_mfma_f32_16x16x32_bf16 v[20:23], v[148:151], v[206:209], v[20:23]
	v_mfma_f32_16x16x32_bf16 v[16:19], v[182:185], v[206:209], v[16:19]
	v_mfma_f32_16x16x32_bf16 v[4:7], v[148:151], v[214:217], v[4:7]
	v_mfma_f32_16x16x32_bf16 v[0:3], v[182:185], v[214:217], v[0:3]
	s_setprio 0
	s_barrier
	s_add_i32 s43, 0, 0x18000
	s_add_i32 s88, 0, 0x1c000
	v_add_u32_e32 v140, s43, v173
	v_add_u32_e32 v156, s88, v173
	ds_read_b128 v[128:131], v140
	ds_read_b128 v[132:135], v140 offset:1024
	ds_read_b128 v[136:139], v140 offset:2048
	ds_read_b128 v[140:143], v140 offset:3072
	ds_read_b128 v[144:147], v156
	ds_read_b128 v[148:151], v156 offset:1024
	ds_read_b128 v[168:171], v156 offset:2048
	ds_read_b128 v[182:185], v156 offset:3072
	s_add_u32 s38, s38, 0x20000
	s_addc_u32 s39, s39, 0
	s_mov_b32 m0, s50
	v_lshl_add_u64 v[226:227], s[38:39], 0, v[152:153]
	ds_read_b128 v[186:189], v177 offset:32768
	ds_read_b128 v[190:193], v177 offset:33792
	ds_read_b128 v[194:197], v177 offset:34816
	ds_read_b128 v[198:201], v177 offset:35840
	ds_read_b128 v[202:205], v177 offset:36864
	ds_read_b128 v[206:209], v177 offset:37888
	ds_read_b128 v[210:213], v177 offset:38912
	ds_read_b128 v[214:217], v177 offset:39936
	global_load_lds_dwordx4 v[226:227], off
	v_lshl_add_u64 v[226:227], s[38:39], 0, v[154:155]
	s_mov_b32 m0, s51
	s_nop 0
	global_load_lds_dwordx4 v[226:227], off
	s_waitcnt vmcnt(8)
	s_waitcnt lgkmcnt(0)
	s_barrier
	s_setprio 1
	v_mfma_f32_16x16x32_bf16 v[124:127], v[128:131], v[186:189], v[124:127]
	v_mfma_f32_16x16x32_bf16 v[120:123], v[136:139], v[186:189], v[120:123]
	v_mfma_f32_16x16x32_bf16 v[112:115], v[128:131], v[194:197], v[112:115]
	v_mfma_f32_16x16x32_bf16 v[116:119], v[136:139], v[194:197], v[116:119]
	v_mfma_f32_16x16x32_bf16 v[96:99], v[128:131], v[202:205], v[96:99]
	v_mfma_f32_16x16x32_bf16 v[104:107], v[136:139], v[202:205], v[104:107]
	v_mfma_f32_16x16x32_bf16 v[76:79], v[128:131], v[210:213], v[76:79]
	v_mfma_f32_16x16x32_bf16 v[72:75], v[136:139], v[210:213], v[72:75]
	v_mfma_f32_16x16x32_bf16 v[124:127], v[132:135], v[190:193], v[124:127]
	v_mfma_f32_16x16x32_bf16 v[120:123], v[140:143], v[190:193], v[120:123]
	v_mfma_f32_16x16x32_bf16 v[112:115], v[132:135], v[198:201], v[112:115]
	v_mfma_f32_16x16x32_bf16 v[116:119], v[140:143], v[198:201], v[116:119]
	v_mfma_f32_16x16x32_bf16 v[96:99], v[132:135], v[206:209], v[96:99]
	v_mfma_f32_16x16x32_bf16 v[104:107], v[140:143], v[206:209], v[104:107]
	v_mfma_f32_16x16x32_bf16 v[76:79], v[132:135], v[214:217], v[76:79]
	v_mfma_f32_16x16x32_bf16 v[72:75], v[140:143], v[214:217], v[72:75]
	s_setprio 0
	s_setprio 1
	v_mfma_f32_16x16x32_bf16 v[108:111], v[144:147], v[186:189], v[108:111]
	v_mfma_f32_16x16x32_bf16 v[100:103], v[168:171], v[186:189], v[100:103]
	v_mfma_f32_16x16x32_bf16 v[88:91], v[144:147], v[194:197], v[88:91]
	v_mfma_f32_16x16x32_bf16 v[92:95], v[168:171], v[194:197], v[92:95]
	v_mfma_f32_16x16x32_bf16 v[84:87], v[144:147], v[202:205], v[84:87]
	v_mfma_f32_16x16x32_bf16 v[80:83], v[168:171], v[202:205], v[80:83]
	v_mfma_f32_16x16x32_bf16 v[68:71], v[144:147], v[210:213], v[68:71]
	v_mfma_f32_16x16x32_bf16 v[64:67], v[168:171], v[210:213], v[64:67]
	v_mfma_f32_16x16x32_bf16 v[108:111], v[148:151], v[190:193], v[108:111]
	v_mfma_f32_16x16x32_bf16 v[100:103], v[182:185], v[190:193], v[100:103]
	v_mfma_f32_16x16x32_bf16 v[88:91], v[148:151], v[198:201], v[88:91]
	v_mfma_f32_16x16x32_bf16 v[92:95], v[182:185], v[198:201], v[92:95]
	v_mfma_f32_16x16x32_bf16 v[84:87], v[148:151], v[206:209], v[84:87]
	v_mfma_f32_16x16x32_bf16 v[80:83], v[182:185], v[206:209], v[80:83]
	v_mfma_f32_16x16x32_bf16 v[68:71], v[148:151], v[214:217], v[68:71]
	v_mfma_f32_16x16x32_bf16 v[64:67], v[182:185], v[214:217], v[64:67]
	s_setprio 0
	s_barrier
	s_add_i32 s38, s43, s47
	v_lshl_add_u64 v[218:219], v[218:219], 0, s[16:17]
	s_mov_b32 m0, s38
	ds_read_b128 v[186:189], v177 offset:49152
	ds_read_b128 v[190:193], v177 offset:50176
	ds_read_b128 v[194:197], v177 offset:51200
	ds_read_b128 v[198:201], v177 offset:52224
	ds_read_b128 v[202:205], v177 offset:53248
	ds_read_b128 v[206:209], v177 offset:54272
	ds_read_b128 v[210:213], v177 offset:55296
	ds_read_b128 v[214:217], v177 offset:56320
	global_load_lds_dwordx4 v[218:219], off
	s_add_i32 m0, s38, 0x2000
	s_add_u32 s36, s36, 0x20080
	v_lshl_add_u64 v[218:219], v[220:221], 0, s[16:17]
	s_addc_u32 s37, s37, 0
	s_add_i32 s38, s88, s47
	global_load_lds_dwordx4 v[218:219], off
	v_lshl_add_u64 v[218:219], s[36:37], 0, v[152:153]
	s_mov_b32 m0, s38
	s_nop 0
	global_load_lds_dwordx4 v[218:219], off
	v_lshl_add_u64 v[218:219], s[36:37], 0, v[154:155]
	s_add_i32 m0, s38, 0x2000
	s_nop 0
	global_load_lds_dwordx4 v[218:219], off
	v_lshl_add_u64 v[218:219], v[222:223], 0, s[16:17]
	s_mov_b32 m0, s61
	s_nop 0
	global_load_lds_dwordx4 v[218:219], off
	v_lshl_add_u64 v[218:219], v[224:225], 0, s[16:17]
	s_mov_b32 m0, s62
	s_nop 0
	global_load_lds_dwordx4 v[218:219], off
	s_waitcnt vmcnt(8)
	s_waitcnt lgkmcnt(0)
	s_barrier
	s_setprio 1
	v_mfma_f32_16x16x32_bf16 v[60:63], v[128:131], v[186:189], v[60:63]
	v_mfma_f32_16x16x32_bf16 v[56:59], v[136:139], v[186:189], v[56:59]
	v_mfma_f32_16x16x32_bf16 v[44:47], v[128:131], v[194:197], v[44:47]
	v_mfma_f32_16x16x32_bf16 v[40:43], v[136:139], v[194:197], v[40:43]
	v_mfma_f32_16x16x32_bf16 v[28:31], v[128:131], v[202:205], v[28:31]
	v_mfma_f32_16x16x32_bf16 v[24:27], v[136:139], v[202:205], v[24:27]
	v_mfma_f32_16x16x32_bf16 v[12:15], v[128:131], v[210:213], v[12:15]
	v_mfma_f32_16x16x32_bf16 v[8:11], v[136:139], v[210:213], v[8:11]
	v_mfma_f32_16x16x32_bf16 v[60:63], v[132:135], v[190:193], v[60:63]
	v_mfma_f32_16x16x32_bf16 v[56:59], v[140:143], v[190:193], v[56:59]
	v_mfma_f32_16x16x32_bf16 v[44:47], v[132:135], v[198:201], v[44:47]
	v_mfma_f32_16x16x32_bf16 v[40:43], v[140:143], v[198:201], v[40:43]
	v_mfma_f32_16x16x32_bf16 v[28:31], v[132:135], v[206:209], v[28:31]
	v_mfma_f32_16x16x32_bf16 v[24:27], v[140:143], v[206:209], v[24:27]
	v_mfma_f32_16x16x32_bf16 v[12:15], v[132:135], v[214:217], v[12:15]
	v_mfma_f32_16x16x32_bf16 v[8:11], v[140:143], v[214:217], v[8:11]
	s_setprio 0
	s_setprio 1
	v_mfma_f32_16x16x32_bf16 v[52:55], v[144:147], v[186:189], v[52:55]
	v_mfma_f32_16x16x32_bf16 v[48:51], v[168:171], v[186:189], v[48:51]
	v_mfma_f32_16x16x32_bf16 v[36:39], v[144:147], v[194:197], v[36:39]
	v_mfma_f32_16x16x32_bf16 v[32:35], v[168:171], v[194:197], v[32:35]
	v_mfma_f32_16x16x32_bf16 v[20:23], v[144:147], v[202:205], v[20:23]
	v_mfma_f32_16x16x32_bf16 v[16:19], v[168:171], v[202:205], v[16:19]
	v_mfma_f32_16x16x32_bf16 v[4:7], v[144:147], v[210:213], v[4:7]
	v_mfma_f32_16x16x32_bf16 v[0:3], v[168:171], v[210:213], v[0:3]
	v_mfma_f32_16x16x32_bf16 v[52:55], v[148:151], v[190:193], v[52:55]
	v_mfma_f32_16x16x32_bf16 v[48:51], v[182:185], v[190:193], v[48:51]
	v_mfma_f32_16x16x32_bf16 v[36:39], v[148:151], v[198:201], v[36:39]
	v_mfma_f32_16x16x32_bf16 v[32:35], v[182:185], v[198:201], v[32:35]
	v_mfma_f32_16x16x32_bf16 v[20:23], v[148:151], v[206:209], v[20:23]
	v_mfma_f32_16x16x32_bf16 v[16:19], v[182:185], v[206:209], v[16:19]
	v_mfma_f32_16x16x32_bf16 v[4:7], v[148:151], v[214:217], v[4:7]
	v_mfma_f32_16x16x32_bf16 v[0:3], v[182:185], v[214:217], v[0:3]
	s_setprio 0
	s_barrier
	s_add_i32 s42, s42, 2
	s_add_u32 s6, s6, 0x100
	s_addc_u32 s7, s7, 0
	s_add_u32 s40, s40, 0x100
	s_addc_u32 s41, s41, 0
	s_cmp_gt_u32 s42, 5
	s_cbranch_scc0 .LBB0_938
	s_and_b64 vcc, exec, s[18:19]
	s_cbranch_vccz .LBB0_941
	s_barrier
